# g1: hoist 34 item-invariant w_gate_up/bias loads out of the item loop (on top of g3 gw hoist + scan rebalance + priorities + wide stores + read split)
# speedup vs baseline: 1.0022x; 1.0022x over previous
; DI void gla_gates(const P& p, int t0, int hh, char* smem, float (&bfv)[16], float (&bbv)[16], float& totf, float& totb) {
;     ...
;   for (int r = 0; r < 16; ++r) {
;     wf[r] = p.w_gu_f[r * 256 + hh * 64 + d];
;     wb[r] = p.w_gu_b[r * 256 + hh * 64 + d];
;   }
;   const float biasf = p.b_g_f[hh * 64 + d], biasb = p.b_g_b[hh * 64 + d];
; DI void phase_rope_g1(const P& p, char* smem) {
;   _Pragma("nounroll") for (int rp = 0; rp < REPG1; ++rp)
;   for (int b0 = 0; b0 < NCHUNK * 4; b0 += VN) { int it = min(b0 + VB, NCHUNK * 4 - 1); gla_g1_item(p, it >> 2, it & 3, smem); }
.LBB0_425:
	s_mov_b64 s[4:5], s[0:1]
	v_mov_b32_e32 v9, 0
	global_load_dwordx4 v[0:3], v9, s[4:5] offset:48
	global_load_dwordx4 v[4:7], v9, s[4:5] offset:64
	global_load_dwordx4 v[22:25], v9, s[4:5] offset:232
	s_load_dword s27, s[0:1], 0x100
	v_and_b32_e32 v15, 0xff, v210
	v_lshlrev_b32_e32 v26, 5, v15
	v_mov_b32_e32 v27, v9
	s_mov_b64 s[40:41], 0x2a100000
	s_waitcnt lgkmcnt(0)
	s_lshl_b32 s58, s27, 1
	v_lshlrev_b32_e32 v8, 8, v210
	v_bfe_u32 v13, v210, 6, 2
	v_bfe_u32 v14, v210, 4, 2
	v_and_b32_e32 v10, 63, v210
	v_and_b32_e32 v16, 15, v210
	v_and_b32_e32 v18, 0x30000, v8
	v_lshlrev_b32_e32 v12, 3, v14
	v_lshlrev_b32_e32 v14, 8, v14
	v_lshlrev_b32_e32 v20, 11, v13
	s_movk_i32 s6, 0x7f
	s_movk_i32 s10, 0x80
	s_movk_i32 s26, 0x90
	v_and_b32_e32 v17, 48, v210
	v_lshlrev_b32_e32 v8, 2, v10
	v_lshlrev_b32_e32 v19, 5, v13
	v_add_u32_e32 v18, 16, v18
	v_or3_b32 v14, v14, v20, v16
	v_lshrrev_b32_e32 v11, 8, v210
	s_mov_b64 s[16:17], 0x34b00000
	v_cmp_gt_u32_e64 s[4:5], 64, v15
	v_cmp_lt_u32_e64 s[6:7], s6, v15
	v_cmp_eq_u32_e64 s[8:9], 3, v13
	v_cmp_gt_u32_e64 s[10:11], s10, v15
	v_lshlrev_b32_e32 v36, 4, v13
	v_cmp_eq_u32_e64 s[12:13], 0, v13
	v_mul_u32_u24_e32 v21, 0x90, v16
	v_or_b32_e32 v37, v19, v16
	v_add_u32_e32 v38, v18, v26
	v_lshl_add_u32 v39, v13, 11, v18
	v_lshl_add_u32 v40, v15, 2, v18
	v_add_u32_e32 v41, v18, v8
	v_mad_u32_u24 v13, v10, s26, v18
	v_add_u32_e32 v15, v18, v17
	v_or_b32_e32 v16, 16, v14
	v_or_b32_e32 v18, 32, v14
	v_or_b32_e32 v20, 48, v14
	s_mov_b32 s33, 0
	s_movk_i32 s52, 0x1000
	s_mov_b32 s53, 0xbfb8aa3b
	s_mov_b32 s54, 0x800000
	s_mov_b32 s55, 0x3f317217
	s_mov_b32 s56, 0x7f800000
	s_mov_b32 s57, 0x3d800000
	v_lshl_add_u32 v11, s2, 1, v11
	v_lshlrev_b32_e32 v12, 1, v12
	v_lshlrev_b32_e32 v14, 1, v14
	v_add_u32_e32 v42, v13, v19
	v_add_u32_e32 v43, v15, v21
	v_lshlrev_b32_e32 v16, 1, v16
	v_lshlrev_b32_e32 v18, 1, v18
	v_lshlrev_b32_e32 v20, 1, v20
	v_mov_b32_e32 v44, 0x41b17218
	s_waitcnt vmcnt(0)
	v_readfirstlane_b32 s29, v3
	v_readfirstlane_b32 s28, v2
	v_readfirstlane_b32 s50, v24
	v_readfirstlane_b32 s51, v25
	s_add_u32 s38, s50, 0xc100000
	s_addc_u32 s39, s51, 0
	v_lshl_add_u64 v[2:3], s[50:51], 0, v[26:27]
	v_lshl_add_u64 v[24:25], v[2:3], 0, s[40:41]
	s_add_u32 s40, s50, 0xe900000
	v_readfirstlane_b32 s36, v22
	s_addc_u32 s41, s51, 0
	v_readfirstlane_b32 s37, v23
	s_add_u32 s42, s36, 0x2800000
	s_addc_u32 s43, s37, 0
	s_add_u32 s44, s36, 0x5000000
	s_addc_u32 s45, s37, 0
	s_add_u32 s46, s36, 0x7800000
	s_addc_u32 s47, s37, 0
	s_add_u32 s48, s50, 0x11100000
	s_addc_u32 s49, s51, 0
	v_readfirstlane_b32 s27, v1
	v_readfirstlane_b32 s26, v0
	v_lshl_add_u64 v[0:1], s[50:51], 0, v[8:9]
	s_add_u32 s50, s50, 0x2ab00000
	v_readfirstlane_b32 s31, v5
	v_readfirstlane_b32 s30, v4
	v_readfirstlane_b32 s35, v7
	v_readfirstlane_b32 s34, v6
	v_lshl_add_u64 v[22:23], v[0:1], 0, s[16:17]
	s_addc_u32 s51, s51, 0
	v_add_u32_e32 v0, s33, v11
	v_min_i32_e32 v0, 0x13ff, v0
	v_and_b32_e32 v8, 3, v0
	v_lshlrev_b32_e32 v15, 6, v8
	v_or_b32_e32 v0, v15, v10
	v_lshlrev_b32_e32 v7, 2, v0
	v_or_b32_e32 v6, 0x1000, v7
	v_or_b32_e32 v30, 0x3000, v7
	v_or_b32_e32 v31, 0x3400, v7
	v_or_b32_e32 v0, 0x3800, v7
	v_or_b32_e32 v1, 0x3c00, v7
	global_load_dword v142, v30, s[30:31]
	global_load_dword v143, v31, s[30:31]
	global_load_dword v144, v0, s[26:27]
	s_nop 0
	global_load_dword v145, v0, s[30:31]
	s_nop 0
	global_load_dword v146, v7, s[26:27]
	global_load_dword v147, v7, s[30:31]
	global_load_dword v148, v7, s[26:27] offset:1024
	global_load_dword v149, v7, s[30:31] offset:1024
	global_load_dword v150, v7, s[26:27] offset:2048
	global_load_dword v151, v7, s[30:31] offset:2048
	global_load_dword v152, v7, s[26:27] offset:3072
	global_load_dword v153, v7, s[28:29]
	global_load_dword v154, v7, s[30:31] offset:3072
	global_load_dword v155, v7, s[34:35]
	global_load_dword v156, v1, s[26:27]
	s_nop 0
	global_load_dword v157, v1, s[30:31]
	s_nop 0
	global_load_dword v158, v6, s[26:27]
	global_load_dword v159, v6, s[30:31]
	v_or_b32_e32 v6, 0x1400, v7
	global_load_dword v160, v6, s[26:27]
	global_load_dword v161, v6, s[30:31]
	v_or_b32_e32 v6, 0x1800, v7
	global_load_dword v162, v6, s[26:27]
	global_load_dword v163, v6, s[30:31]
	v_or_b32_e32 v6, 0x1c00, v7
	global_load_dword v164, v6, s[26:27]
	global_load_dword v165, v6, s[30:31]
	v_or_b32_e32 v6, 0x2000, v7
	global_load_dword v166, v6, s[26:27]
	global_load_dword v167, v6, s[30:31]
	v_or_b32_e32 v6, 0x2400, v7
	global_load_dword v168, v6, s[26:27]
	global_load_dword v169, v6, s[30:31]
	v_or_b32_e32 v6, 0x2800, v7
	global_load_dword v170, v6, s[26:27]
	s_nop 0
	global_load_dword v171, v6, s[30:31]
	v_or_b32_e32 v7, 0x2c00, v7
	global_load_dword v172, v7, s[26:27]
	s_nop 0
	global_load_dword v173, v7, s[30:31]
	s_nop 0
	global_load_dword v174, v30, s[26:27]
	s_nop 0
	global_load_dword v175, v31, s[26:27]
	s_waitcnt vmcnt(0)
	s_branch .LBB0_427

; DI void gla_gates(const P& p, int t0, int hh, char* smem, float (&bfv)[16], float (&bbv)[16], float& totf, float& totb) {
;   const int tid = VT, d = tid & 63, tg = tid >> 6;
;   float* gs = (float*)(smem + GL_GS);
;   float* tots = (float*)(smem + GL_TOT);
;   const float* gates = (const float*)(p.ws + OFF_GATES) + (long)t0 * 32;
;   __syncthreads();
;   ((f4*)gs)[tid * 2] = ((const f4*)gates)[tid * 2];
;   ((f4*)gs)[tid * 2 + 1] = ((const f4*)gates)[tid * 2 + 1];
;   float wf[16], wb[16];
; #pragma unroll
;   for (int r = 0; r < 16; ++r) {
;     wf[r] = p.w_gu_f[r * 256 + hh * 64 + d];
;     wb[r] = p.w_gu_b[r * 256 + hh * 64 + d];
;   }
;   const float biasf = p.b_g_f[hh * 64 + d], biasb = p.b_g_b[hh * 64 + d];
;   __syncthreads();
; #pragma unroll
;   for (int j = 0; j < 16; ++j) {
;     const float* gr = gs + (tg * 16 + j) * 32;
;     float zf = biasf, zb = biasb;
; #pragma unroll
;     for (int r = 0; r < 16; ++r) { zf += gr[r] * wf[r]; zb += gr[16 + r] * wb[r]; }
.LBB0_427:
	v_add_u32_e32 v0, s33, v11
	v_min_i32_e32 v0, 0x13ff, v0
	v_ashrrev_i32_e32 v13, 2, v0
	v_lshlrev_b32_e32 v26, 6, v13
	v_ashrrev_i32_e32 v27, 31, v26
	v_and_b32_e32 v8, 3, v0
	v_lshlrev_b64 v[0:1], 7, v[26:27]
	v_lshl_add_u64 v[0:1], v[24:25], 0, v[0:1]
	s_barrier
	global_load_dwordx4 v[60:63], v[0:1], off offset:16
	global_load_dwordx4 v[64:67], v[0:1], off
	v_lshlrev_b32_e32 v15, 6, v8
	v_or_b32_e32 v0, v15, v10
	v_lshlrev_b32_e32 v7, 2, v0
	v_or_b32_e32 v6, 0x1000, v7
	v_or_b32_e32 v30, 0x3000, v7
	v_or_b32_e32 v31, 0x3400, v7
	v_or_b32_e32 v0, 0x3800, v7
	v_or_b32_e32 v1, 0x3c00, v7
	v_mov_b32_e32 v2, v142
	v_mov_b32_e32 v3, v143
	v_mov_b32_e32 v4, v144
	s_nop 0
	v_mov_b32_e32 v0, v145
	s_nop 0
	v_mov_b32_e32 v52, v146
	v_mov_b32_e32 v46, v147
	v_mov_b32_e32 v47, v148
	v_mov_b32_e32 v48, v149
	v_mov_b32_e32 v49, v150
	v_mov_b32_e32 v50, v151
	v_mov_b32_e32 v51, v152
	v_mov_b32_e32 v19, v153
	v_mov_b32_e32 v53, v154
	v_mov_b32_e32 v17, v155
	v_mov_b32_e32 v5, v156
	s_nop 0
	v_mov_b32_e32 v1, v157
	s_nop 0
	v_mov_b32_e32 v59, v158
	v_mov_b32_e32 v57, v159
	v_or_b32_e32 v6, 0x1400, v7
	v_mov_b32_e32 v58, v160
	v_mov_b32_e32 v55, v161
	v_or_b32_e32 v6, 0x1800, v7
	v_mov_b32_e32 v56, v162
	v_mov_b32_e32 v54, v163
	v_or_b32_e32 v6, 0x1c00, v7
	v_mov_b32_e32 v21, v164
	v_mov_b32_e32 v45, v165
	v_or_b32_e32 v6, 0x2000, v7
	v_mov_b32_e32 v34, v166
	v_mov_b32_e32 v28, v167
	v_or_b32_e32 v6, 0x2400, v7
	v_mov_b32_e32 v35, v168
	v_mov_b32_e32 v29, v169
	v_or_b32_e32 v6, 0x2800, v7
	v_mov_b32_e32 v32, v170
	s_nop 0
	v_mov_b32_e32 v6, v171
	v_or_b32_e32 v7, 0x2c00, v7
	v_mov_b32_e32 v33, v172
	s_nop 0
	v_mov_b32_e32 v7, v173
	s_nop 0
	v_mov_b32_e32 v30, v174
	s_nop 0
	v_mov_b32_e32 v31, v175
	s_waitcnt vmcnt(0)
	ds_write_b128 v38, v[64:67]
	ds_write_b128 v38, v[60:63] offset:16
	s_waitcnt lgkmcnt(0)
	s_barrier
	ds_read_b128 v[60:63], v39
	ds_read_b128 v[64:67], v39 offset:16
	ds_read_b128 v[68:71], v39 offset:64
	ds_read_b128 v[72:75], v39 offset:96
	ds_read_b128 v[76:79], v39 offset:112
	ds_read_b128 v[80:83], v39 offset:32
	ds_read_b128 v[84:87], v39 offset:48
	ds_read_b128 v[88:91], v39 offset:80
	s_waitcnt vmcnt(22) lgkmcnt(7)
	v_fma_f32 v60, v52, v60, v19
	v_fmac_f32_e32 v60, v47, v61
	v_fmac_f32_e32 v60, v49, v62
	v_fmac_f32_e32 v60, v51, v63
	s_waitcnt vmcnt(20) lgkmcnt(5)
	v_fma_f32 v68, v46, v68, v17
	s_waitcnt vmcnt(17)
	v_fmac_f32_e32 v60, v59, v64
	v_fmac_f32_e32 v68, v48, v69
	s_waitcnt vmcnt(15)
	v_fmac_f32_e32 v60, v58, v65
	v_fmac_f32_e32 v68, v50, v70
	s_waitcnt vmcnt(13)
	v_fmac_f32_e32 v60, v56, v66
	v_fmac_f32_e32 v68, v53, v71
	s_waitcnt vmcnt(11)
	v_fmac_f32_e32 v60, v21, v67
	s_waitcnt lgkmcnt(0)
	v_fmac_f32_e32 v68, v57, v88
	s_waitcnt vmcnt(9)
	v_fmac_f32_e32 v60, v34, v80
	v_fmac_f32_e32 v68, v55, v89
	s_waitcnt vmcnt(7)
	v_fmac_f32_e32 v60, v35, v81
	v_fmac_f32_e32 v68, v54, v90
	s_waitcnt vmcnt(5)
	v_fmac_f32_e32 v60, v32, v82
	s_waitcnt vmcnt(3)
	v_fmac_f32_e32 v60, v33, v83
	s_waitcnt vmcnt(1)
	v_fmac_f32_e32 v60, v30, v84
	v_pk_mul_f32 v[86:87], v[4:5], v[86:87]
	v_fmac_f32_e32 v68, v45, v91
	s_waitcnt vmcnt(0)
	v_fmac_f32_e32 v60, v31, v85
	v_fmac_f32_e32 v68, v28, v72
	v_add_f32_e32 v60, v60, v86
	v_fmac_f32_e32 v68, v29, v73
	v_add_f32_e32 v60, v60, v87
	v_fmac_f32_e32 v68, v6, v74
	v_mul_f32_e64 v62, |v60|, s53
	v_pk_mul_f32 v[76:77], v[2:3], v[76:77]
	v_fmac_f32_e32 v68, v7, v75
	v_exp_f32_e32 v62, v62
	v_add_f32_e32 v61, v68, v76
	v_pk_mul_f32 v[78:79], v[0:1], v[78:79]
	v_add_f32_e32 v61, v61, v77
	v_add_f32_e32 v61, v61, v78
	v_add_f32_e32 v63, v61, v79
	v_add_f32_e32 v61, 1.0, v62
	v_cmp_gt_f32_e32 vcc, s54, v61
	v_min_f32_e32 v60, 0, v60
	ds_read_b128 v[74:77], v39 offset:208
	v_cndmask_b32_e64 v62, 0, 32, vcc
	v_ldexp_f32 v61, v61, v62
	v_log_f32_e32 v61, v61
	v_mul_f32_e64 v62, |v63|, s53
	v_exp_f32_e32 v62, v62
	v_mul_f32_e32 v64, 0x3f317217, v61
	v_fma_f32 v64, v61, s55, -v64
	v_fmac_f32_e32 v64, 0x3377d1cf, v61
	v_fmac_f32_e32 v64, 0x3f317217, v61
	v_cmp_lt_f32_e64 s[16:17], |v61|, s56
	v_add_f32_e32 v62, 1.0, v62
	s_nop 0
	v_cndmask_b32_e64 v61, v61, v64, s[16:17]
	v_cndmask_b32_e32 v64, 0, v44, vcc
	v_cmp_gt_f32_e32 vcc, s54, v62
	v_sub_f32_e32 v61, v61, v64
	v_sub_f32_e32 v61, v60, v61
	v_cndmask_b32_e64 v65, 0, 32, vcc
	v_ldexp_f32 v62, v62, v65
	v_log_f32_e32 v62, v62
	v_min_f32_e32 v60, 0, v63
	v_cndmask_b32_e32 v67, 0, v44, vcc
	v_mul_f32_e32 v63, 0x3f317217, v62
	v_fma_f32 v63, v62, s55, -v63
	v_fmac_f32_e32 v63, 0x3377d1cf, v62
	v_fmac_f32_e32 v63, 0x3f317217, v62
	v_cmp_lt_f32_e64 s[16:17], |v62|, s56
	s_nop 1
	v_cndmask_b32_e64 v66, v62, v63, s[16:17]
	ds_read_b128 v[62:65], v39 offset:128
	v_sub_f32_e32 v70, v66, v67
	v_sub_f32_e32 v60, v60, v70
	ds_read_b128 v[70:73], v39 offset:144
	ds_read_b128 v[66:69], v39 offset:192
	s_waitcnt lgkmcnt(2)
	v_fma_f32 v78, v52, v62, v19
	v_fmac_f32_e32 v78, v47, v63
	v_fmac_f32_e32 v78, v49, v64
	v_fmac_f32_e32 v78, v51, v65
	ds_read_b128 v[62:65], v39 offset:160
	s_waitcnt lgkmcnt(2)
	v_fmac_f32_e32 v78, v59, v70
	v_fmac_f32_e32 v78, v58, v71
	v_fmac_f32_e32 v78, v56, v72
	v_fmac_f32_e32 v78, v21, v73
	ds_read_b128 v[70:73], v39 offset:176
	s_waitcnt lgkmcnt(1)
	v_fmac_f32_e32 v78, v34, v62
	v_fmac_f32_e32 v78, v35, v63
	v_fma_f32 v79, v46, v66, v17
	v_fmac_f32_e32 v78, v32, v64
	v_fmac_f32_e32 v79, v48, v67
	v_fmac_f32_e32 v78, v33, v65
	v_fmac_f32_e32 v79, v50, v68
	s_waitcnt lgkmcnt(0)
	v_fmac_f32_e32 v78, v30, v70
	v_fmac_f32_e32 v79, v53, v69
	v_fmac_f32_e32 v78, v31, v71
	v_pk_mul_f32 v[64:65], v[4:5], v[72:73]
	v_fmac_f32_e32 v79, v57, v74
	ds_read_b128 v[66:69], v39 offset:224
	v_add_f32_e32 v64, v78, v64
	v_fmac_f32_e32 v79, v55, v75
	v_add_f32_e32 v64, v64, v65
	v_fmac_f32_e32 v79, v54, v76
	v_mul_f32_e64 v65, |v64|, s53
	v_fmac_f32_e32 v79, v45, v77
	ds_read_b128 v[74:77], v39 offset:240
	v_exp_f32_e32 v65, v65
	s_waitcnt lgkmcnt(1)
; DI float log_sigmoid(float z) { return fminf(z, 0.f) - __logf(1.f + fexp(-fabsf(z))); }
; DI void gla_gates(const P& p, int t0, int hh, char* smem, float (&bfv)[16], float (&bbv)[16], float& totf, float& totb) {
;     ...
; #pragma unroll
;   for (int j = 0; j < 16; ++j) {
;     const float* gr = gs + (tg * 16 + j) * 32;
;     float zf = biasf, zb = biasb;
; #pragma unroll
;     for (int r = 0; r < 16; ++r) { zf += gr[r] * wf[r]; zb += gr[16 + r] * wb[r]; }
;     bfv[j] = log_sigmoid(zf) * (1.f / 16.f);
;     bbv[j] = log_sigmoid(zb) * (1.f / 16.f);
;   }
	v_fmac_f32_e32 v79, v28, v66
	v_fmac_f32_e32 v79, v29, v67
	v_fmac_f32_e32 v79, v6, v68
	v_add_f32_e32 v65, 1.0, v65
	v_fmac_f32_e32 v79, v7, v69
	s_waitcnt lgkmcnt(0)
	v_pk_mul_f32 v[62:63], v[2:3], v[74:75]
	v_cmp_gt_f32_e32 vcc, s54, v65
	v_add_f32_e32 v62, v79, v62
	v_add_f32_e32 v66, v62, v63
	v_cndmask_b32_e64 v67, 0, 32, vcc
	v_pk_mul_f32 v[62:63], v[0:1], v[76:77]
	v_ldexp_f32 v65, v65, v67
	v_log_f32_e32 v65, v65
	v_add_f32_e32 v62, v66, v62
	v_add_f32_e32 v62, v62, v63
	v_mul_f32_e64 v66, |v62|, s53
	v_exp_f32_e32 v66, v66
	v_min_f32_e32 v63, 0, v64
	v_mul_f32_e32 v64, 0x3f317217, v65
	v_fma_f32 v64, v65, s55, -v64
	v_fmac_f32_e32 v64, 0x3377d1cf, v65
	v_fmac_f32_e32 v64, 0x3f317217, v65
	v_cmp_lt_f32_e64 s[16:17], |v65|, s56
	v_add_f32_e32 v66, 1.0, v66
	v_min_f32_e32 v62, 0, v62
	v_cndmask_b32_e64 v64, v65, v64, s[16:17]
	v_cndmask_b32_e32 v65, 0, v44, vcc
	v_cmp_gt_f32_e32 vcc, s54, v66
	v_sub_f32_e32 v64, v64, v65
	v_sub_f32_e32 v63, v63, v64
	v_cndmask_b32_e64 v67, 0, 32, vcc
	v_ldexp_f32 v66, v66, v67
	v_log_f32_e32 v66, v66
	v_cndmask_b32_e32 v69, 0, v44, vcc
	ds_read_b128 v[76:79], v39 offset:336
	v_mul_f32_e32 v64, 0x3f317217, v66
	v_fma_f32 v64, v66, s55, -v64
	v_fmac_f32_e32 v64, 0x3377d1cf, v66
	v_fmac_f32_e32 v64, 0x3f317217, v66
	v_cmp_lt_f32_e64 s[16:17], |v66|, s56
	s_nop 1
	v_cndmask_b32_e64 v68, v66, v64, s[16:17]
	ds_read_b128 v[64:67], v39 offset:256
	v_sub_f32_e32 v72, v68, v69
	v_sub_f32_e32 v62, v62, v72
	ds_read_b128 v[72:75], v39 offset:272
	ds_read_b128 v[68:71], v39 offset:320
	s_waitcnt lgkmcnt(2)
	v_fma_f32 v80, v52, v64, v19
	v_fmac_f32_e32 v80, v47, v65
	v_fmac_f32_e32 v80, v49, v66
	v_fmac_f32_e32 v80, v51, v67
	ds_read_b128 v[64:67], v39 offset:288
	s_waitcnt lgkmcnt(2)
	v_fmac_f32_e32 v80, v59, v72
	v_fmac_f32_e32 v80, v58, v73
	v_fmac_f32_e32 v80, v56, v74
	v_fmac_f32_e32 v80, v21, v75
	ds_read_b128 v[72:75], v39 offset:304
	s_waitcnt lgkmcnt(1)
	v_fmac_f32_e32 v80, v34, v64
	v_fmac_f32_e32 v80, v35, v65
	v_fma_f32 v81, v46, v68, v17
	v_fmac_f32_e32 v80, v32, v66
	v_fmac_f32_e32 v81, v48, v69
	v_fmac_f32_e32 v80, v33, v67
	v_fmac_f32_e32 v81, v50, v70
	s_waitcnt lgkmcnt(0)
	v_fmac_f32_e32 v80, v30, v72
	v_fmac_f32_e32 v81, v53, v71
	v_fmac_f32_e32 v80, v31, v73
	v_pk_mul_f32 v[66:67], v[4:5], v[74:75]
	v_fmac_f32_e32 v81, v57, v76
	ds_read_b128 v[68:71], v39 offset:352
	v_add_f32_e32 v66, v80, v66
	v_fmac_f32_e32 v81, v55, v77
	v_add_f32_e32 v66, v66, v67
	v_fmac_f32_e32 v81, v54, v78
	v_mul_f32_e64 v67, |v66|, s53
	v_fmac_f32_e32 v81, v45, v79
	ds_read_b128 v[76:79], v39 offset:368
	v_exp_f32_e32 v67, v67
	s_waitcnt lgkmcnt(1)
	v_fmac_f32_e32 v81, v28, v68
	v_fmac_f32_e32 v81, v29, v69
	v_fmac_f32_e32 v81, v6, v70
	v_add_f32_e32 v67, 1.0, v67
	v_fmac_f32_e32 v81, v7, v71
	s_waitcnt lgkmcnt(0)
	v_pk_mul_f32 v[64:65], v[2:3], v[76:77]
	v_cmp_gt_f32_e32 vcc, s54, v67
	v_add_f32_e32 v64, v81, v64
	v_add_f32_e32 v68, v64, v65
	v_cndmask_b32_e64 v69, 0, 32, vcc
	v_pk_mul_f32 v[64:65], v[0:1], v[78:79]
	v_ldexp_f32 v67, v67, v69
	v_log_f32_e32 v67, v67
	v_add_f32_e32 v64, v68, v64
	v_add_f32_e32 v64, v64, v65
	v_mul_f32_e64 v68, |v64|, s53
	v_exp_f32_e32 v68, v68
	v_min_f32_e32 v65, 0, v66
	v_mul_f32_e32 v66, 0x3f317217, v67
	v_fma_f32 v66, v67, s55, -v66
	v_fmac_f32_e32 v66, 0x3377d1cf, v67
	v_fmac_f32_e32 v66, 0x3f317217, v67
	v_cmp_lt_f32_e64 s[16:17], |v67|, s56
	v_add_f32_e32 v68, 1.0, v68
	v_min_f32_e32 v64, 0, v64
	v_cndmask_b32_e64 v66, v67, v66, s[16:17]
	v_cndmask_b32_e32 v67, 0, v44, vcc
	v_cmp_gt_f32_e32 vcc, s54, v68
	v_sub_f32_e32 v66, v66, v67
	v_sub_f32_e32 v65, v65, v66
	v_cndmask_b32_e64 v69, 0, 32, vcc
	v_ldexp_f32 v68, v68, v69
	v_log_f32_e32 v68, v68
	v_cndmask_b32_e32 v71, 0, v44, vcc
	ds_read_b128 v[78:81], v39 offset:464
	v_mul_f32_e32 v66, 0x3f317217, v68
	v_fma_f32 v66, v68, s55, -v66
	v_fmac_f32_e32 v66, 0x3377d1cf, v68
	v_fmac_f32_e32 v66, 0x3f317217, v68
	v_cmp_lt_f32_e64 s[16:17], |v68|, s56
	s_nop 1
	v_cndmask_b32_e64 v70, v68, v66, s[16:17]
	ds_read_b128 v[66:69], v39 offset:384
	v_sub_f32_e32 v74, v70, v71
	v_sub_f32_e32 v64, v64, v74
	ds_read_b128 v[74:77], v39 offset:400
	ds_read_b128 v[70:73], v39 offset:448
	s_waitcnt lgkmcnt(2)
	v_fma_f32 v82, v52, v66, v19
	v_fmac_f32_e32 v82, v47, v67
	v_fmac_f32_e32 v82, v49, v68
	v_fmac_f32_e32 v82, v51, v69
	ds_read_b128 v[66:69], v39 offset:416
	s_waitcnt lgkmcnt(2)
	v_fmac_f32_e32 v82, v59, v74
	v_fmac_f32_e32 v82, v58, v75
	v_fmac_f32_e32 v82, v56, v76
	v_fmac_f32_e32 v82, v21, v77
	ds_read_b128 v[74:77], v39 offset:432
	s_waitcnt lgkmcnt(1)
	v_fmac_f32_e32 v82, v34, v66
	v_fmac_f32_e32 v82, v35, v67
	v_fma_f32 v83, v46, v70, v17
	v_fmac_f32_e32 v82, v32, v68
	v_fmac_f32_e32 v83, v48, v71
	v_fmac_f32_e32 v82, v33, v69
	v_fmac_f32_e32 v83, v50, v72
	s_waitcnt lgkmcnt(0)
	v_fmac_f32_e32 v82, v30, v74
	v_fmac_f32_e32 v83, v53, v73
	v_fmac_f32_e32 v82, v31, v75
	v_pk_mul_f32 v[68:69], v[4:5], v[76:77]
	v_fmac_f32_e32 v83, v57, v78
	ds_read_b128 v[70:73], v39 offset:480
	v_add_f32_e32 v68, v82, v68
	v_fmac_f32_e32 v83, v55, v79
	v_add_f32_e32 v68, v68, v69
	v_fmac_f32_e32 v83, v54, v80
	v_mul_f32_e64 v69, |v68|, s53
	v_fmac_f32_e32 v83, v45, v81
	ds_read_b128 v[78:81], v39 offset:496
	v_exp_f32_e32 v69, v69
	s_waitcnt lgkmcnt(1)
	v_fmac_f32_e32 v83, v28, v70
	v_fmac_f32_e32 v83, v29, v71
	v_fmac_f32_e32 v83, v6, v72
	v_add_f32_e32 v69, 1.0, v69
	v_fmac_f32_e32 v83, v7, v73
	s_waitcnt lgkmcnt(0)
; DI float log_sigmoid(float z) { return fminf(z, 0.f) - __logf(1.f + fexp(-fabsf(z))); }
; DI void gla_gates(const P& p, int t0, int hh, char* smem, float (&bfv)[16], float (&bbv)[16], float& totf, float& totb) {
;     ...
; #pragma unroll
;   for (int j = 0; j < 16; ++j) {
;     const float* gr = gs + (tg * 16 + j) * 32;
;     float zf = biasf, zb = biasb;
; #pragma unroll
;     for (int r = 0; r < 16; ++r) { zf += gr[r] * wf[r]; zb += gr[16 + r] * wb[r]; }
;     bfv[j] = log_sigmoid(zf) * (1.f / 16.f);
;     bbv[j] = log_sigmoid(zb) * (1.f / 16.f);
;   }
	v_pk_mul_f32 v[66:67], v[2:3], v[78:79]
	v_cmp_gt_f32_e32 vcc, s54, v69
	v_add_f32_e32 v66, v83, v66
	v_add_f32_e32 v70, v66, v67
	v_cndmask_b32_e64 v71, 0, 32, vcc
	v_pk_mul_f32 v[66:67], v[0:1], v[80:81]
	v_ldexp_f32 v69, v69, v71
	v_log_f32_e32 v69, v69
	v_add_f32_e32 v66, v70, v66
	v_add_f32_e32 v66, v66, v67
	v_mul_f32_e64 v70, |v66|, s53
	v_exp_f32_e32 v70, v70
	v_min_f32_e32 v67, 0, v68
	v_mul_f32_e32 v68, 0x3f317217, v69
	v_fma_f32 v68, v69, s55, -v68
	v_fmac_f32_e32 v68, 0x3377d1cf, v69
	v_fmac_f32_e32 v68, 0x3f317217, v69
	v_cmp_lt_f32_e64 s[16:17], |v69|, s56
	v_add_f32_e32 v70, 1.0, v70
	v_min_f32_e32 v66, 0, v66
	v_cndmask_b32_e64 v68, v69, v68, s[16:17]
	v_cndmask_b32_e32 v69, 0, v44, vcc
	v_cmp_gt_f32_e32 vcc, s54, v70
	v_sub_f32_e32 v68, v68, v69
	v_sub_f32_e32 v67, v67, v68
	v_cndmask_b32_e64 v71, 0, 32, vcc
	v_ldexp_f32 v70, v70, v71
	v_log_f32_e32 v70, v70
	v_cndmask_b32_e32 v73, 0, v44, vcc
	ds_read_b128 v[80:83], v39 offset:592
	v_mul_f32_e32 v68, 0x3f317217, v70
	v_fma_f32 v68, v70, s55, -v68
	v_fmac_f32_e32 v68, 0x3377d1cf, v70
	v_fmac_f32_e32 v68, 0x3f317217, v70
	v_cmp_lt_f32_e64 s[16:17], |v70|, s56
	s_nop 1
	v_cndmask_b32_e64 v72, v70, v68, s[16:17]
	ds_read_b128 v[68:71], v39 offset:512
	v_sub_f32_e32 v76, v72, v73
	v_sub_f32_e32 v66, v66, v76
	ds_read_b128 v[76:79], v39 offset:528
	ds_read_b128 v[72:75], v39 offset:576
	s_waitcnt lgkmcnt(2)
	v_fma_f32 v84, v52, v68, v19
	v_fmac_f32_e32 v84, v47, v69
	v_fmac_f32_e32 v84, v49, v70
	v_fmac_f32_e32 v84, v51, v71
	ds_read_b128 v[68:71], v39 offset:544
	s_waitcnt lgkmcnt(2)
	v_fmac_f32_e32 v84, v59, v76
	v_fmac_f32_e32 v84, v58, v77
	v_fmac_f32_e32 v84, v56, v78
	v_fmac_f32_e32 v84, v21, v79
	ds_read_b128 v[76:79], v39 offset:560
	s_waitcnt lgkmcnt(1)
	v_fmac_f32_e32 v84, v34, v68
	v_fmac_f32_e32 v84, v35, v69
	v_fma_f32 v85, v46, v72, v17
	v_fmac_f32_e32 v84, v32, v70
	v_fmac_f32_e32 v85, v48, v73
	v_fmac_f32_e32 v84, v33, v71
	v_fmac_f32_e32 v85, v50, v74
	s_waitcnt lgkmcnt(0)
	v_fmac_f32_e32 v84, v30, v76
	v_fmac_f32_e32 v85, v53, v75
	v_fmac_f32_e32 v84, v31, v77
	v_pk_mul_f32 v[70:71], v[4:5], v[78:79]
	v_fmac_f32_e32 v85, v57, v80
	ds_read_b128 v[72:75], v39 offset:608
	v_add_f32_e32 v70, v84, v70
	v_fmac_f32_e32 v85, v55, v81
	v_add_f32_e32 v70, v70, v71
	v_fmac_f32_e32 v85, v54, v82
	v_mul_f32_e64 v71, |v70|, s53
	v_fmac_f32_e32 v85, v45, v83
	ds_read_b128 v[80:83], v39 offset:624
	v_exp_f32_e32 v71, v71
	s_waitcnt lgkmcnt(1)
	v_fmac_f32_e32 v85, v28, v72
	v_fmac_f32_e32 v85, v29, v73
	v_fmac_f32_e32 v85, v6, v74
	v_add_f32_e32 v71, 1.0, v71
	v_fmac_f32_e32 v85, v7, v75
	s_waitcnt lgkmcnt(0)
	v_pk_mul_f32 v[68:69], v[2:3], v[80:81]
	v_cmp_gt_f32_e32 vcc, s54, v71
	v_add_f32_e32 v68, v85, v68
	v_add_f32_e32 v72, v68, v69
	v_cndmask_b32_e64 v73, 0, 32, vcc
	v_pk_mul_f32 v[68:69], v[0:1], v[82:83]
	v_ldexp_f32 v71, v71, v73
	v_log_f32_e32 v71, v71
	v_add_f32_e32 v68, v72, v68
	v_add_f32_e32 v68, v68, v69
	v_mul_f32_e64 v72, |v68|, s53
	v_exp_f32_e32 v72, v72
	v_min_f32_e32 v69, 0, v70
	v_mul_f32_e32 v70, 0x3f317217, v71
	v_fma_f32 v70, v71, s55, -v70
	v_fmac_f32_e32 v70, 0x3377d1cf, v71
	v_fmac_f32_e32 v70, 0x3f317217, v71
	v_cmp_lt_f32_e64 s[16:17], |v71|, s56
	v_add_f32_e32 v72, 1.0, v72
	v_min_f32_e32 v68, 0, v68
	v_cndmask_b32_e64 v70, v71, v70, s[16:17]
	v_cndmask_b32_e32 v71, 0, v44, vcc
	v_cmp_gt_f32_e32 vcc, s54, v72
	v_sub_f32_e32 v70, v70, v71
	v_sub_f32_e32 v69, v69, v70
	v_cndmask_b32_e64 v73, 0, 32, vcc
	v_ldexp_f32 v72, v72, v73
	v_log_f32_e32 v72, v72
	v_cndmask_b32_e32 v75, 0, v44, vcc
	ds_read_b128 v[82:85], v39 offset:720
	v_mul_f32_e32 v70, 0x3f317217, v72
	v_fma_f32 v70, v72, s55, -v70
	v_fmac_f32_e32 v70, 0x3377d1cf, v72
	v_fmac_f32_e32 v70, 0x3f317217, v72
	v_cmp_lt_f32_e64 s[16:17], |v72|, s56
	s_nop 1
	v_cndmask_b32_e64 v74, v72, v70, s[16:17]
	ds_read_b128 v[70:73], v39 offset:640
	v_sub_f32_e32 v78, v74, v75
	v_sub_f32_e32 v68, v68, v78
	ds_read_b128 v[78:81], v39 offset:656
	ds_read_b128 v[74:77], v39 offset:704
	s_waitcnt lgkmcnt(2)
	v_fma_f32 v86, v52, v70, v19
	v_fmac_f32_e32 v86, v47, v71
	v_fmac_f32_e32 v86, v49, v72
	v_fmac_f32_e32 v86, v51, v73
	ds_read_b128 v[70:73], v39 offset:672
	s_waitcnt lgkmcnt(2)
	v_fmac_f32_e32 v86, v59, v78
	v_fmac_f32_e32 v86, v58, v79
	v_fmac_f32_e32 v86, v56, v80
	v_fmac_f32_e32 v86, v21, v81
	ds_read_b128 v[78:81], v39 offset:688
	s_waitcnt lgkmcnt(1)
	v_fmac_f32_e32 v86, v34, v70
	v_fmac_f32_e32 v86, v35, v71
	v_fma_f32 v87, v46, v74, v17
	v_fmac_f32_e32 v86, v32, v72
	v_fmac_f32_e32 v87, v48, v75
	v_fmac_f32_e32 v86, v33, v73
	v_fmac_f32_e32 v87, v50, v76
	s_waitcnt lgkmcnt(0)
	v_fmac_f32_e32 v86, v30, v78
	v_fmac_f32_e32 v87, v53, v77
	v_fmac_f32_e32 v86, v31, v79
	v_pk_mul_f32 v[72:73], v[4:5], v[80:81]
	v_fmac_f32_e32 v87, v57, v82
	ds_read_b128 v[74:77], v39 offset:736
	v_add_f32_e32 v72, v86, v72
	v_fmac_f32_e32 v87, v55, v83
	v_add_f32_e32 v72, v72, v73
	v_fmac_f32_e32 v87, v54, v84
	v_mul_f32_e64 v73, |v72|, s53
	v_fmac_f32_e32 v87, v45, v85
	ds_read_b128 v[82:85], v39 offset:752
	v_exp_f32_e32 v73, v73
	s_waitcnt lgkmcnt(1)
	v_fmac_f32_e32 v87, v28, v74
	v_fmac_f32_e32 v87, v29, v75
	v_fmac_f32_e32 v87, v6, v76
	v_add_f32_e32 v73, 1.0, v73
	v_fmac_f32_e32 v87, v7, v77
	s_waitcnt lgkmcnt(0)
; DI float log_sigmoid(float z) { return fminf(z, 0.f) - __logf(1.f + fexp(-fabsf(z))); }
; DI void gla_gates(const P& p, int t0, int hh, char* smem, float (&bfv)[16], float (&bbv)[16], float& totf, float& totb) {
;     ...
; #pragma unroll
;   for (int j = 0; j < 16; ++j) {
;     const float* gr = gs + (tg * 16 + j) * 32;
;     float zf = biasf, zb = biasb;
; #pragma unroll
;     for (int r = 0; r < 16; ++r) { zf += gr[r] * wf[r]; zb += gr[16 + r] * wb[r]; }
;     bfv[j] = log_sigmoid(zf) * (1.f / 16.f);
;     bbv[j] = log_sigmoid(zb) * (1.f / 16.f);
;   }
	v_pk_mul_f32 v[70:71], v[2:3], v[82:83]
	v_cmp_gt_f32_e32 vcc, s54, v73
	v_add_f32_e32 v70, v87, v70
	v_add_f32_e32 v74, v70, v71
	v_cndmask_b32_e64 v75, 0, 32, vcc
	v_pk_mul_f32 v[70:71], v[0:1], v[84:85]
	v_ldexp_f32 v73, v73, v75
	v_log_f32_e32 v73, v73
	v_add_f32_e32 v70, v74, v70
	v_add_f32_e32 v70, v70, v71
	v_mul_f32_e64 v74, |v70|, s53
	v_exp_f32_e32 v74, v74
	v_min_f32_e32 v71, 0, v72
	v_mul_f32_e32 v72, 0x3f317217, v73
	v_fma_f32 v72, v73, s55, -v72
	v_fmac_f32_e32 v72, 0x3377d1cf, v73
	v_fmac_f32_e32 v72, 0x3f317217, v73
	v_cmp_lt_f32_e64 s[16:17], |v73|, s56
	v_add_f32_e32 v74, 1.0, v74
	v_min_f32_e32 v70, 0, v70
	v_cndmask_b32_e64 v72, v73, v72, s[16:17]
	v_cndmask_b32_e32 v73, 0, v44, vcc
	v_cmp_gt_f32_e32 vcc, s54, v74
	v_sub_f32_e32 v72, v72, v73
	v_sub_f32_e32 v71, v71, v72
	v_cndmask_b32_e64 v75, 0, 32, vcc
	v_ldexp_f32 v74, v74, v75
	v_log_f32_e32 v74, v74
	v_cndmask_b32_e32 v77, 0, v44, vcc
	ds_read_b128 v[84:87], v39 offset:848
	v_mul_f32_e32 v72, 0x3f317217, v74
	v_fma_f32 v72, v74, s55, -v72
	v_fmac_f32_e32 v72, 0x3377d1cf, v74
	v_fmac_f32_e32 v72, 0x3f317217, v74
	v_cmp_lt_f32_e64 s[16:17], |v74|, s56
	s_nop 1
	v_cndmask_b32_e64 v76, v74, v72, s[16:17]
	ds_read_b128 v[72:75], v39 offset:768
	v_sub_f32_e32 v80, v76, v77
	v_sub_f32_e32 v70, v70, v80
	ds_read_b128 v[80:83], v39 offset:784
	ds_read_b128 v[76:79], v39 offset:832
	s_waitcnt lgkmcnt(2)
	v_fma_f32 v88, v52, v72, v19
	v_fmac_f32_e32 v88, v47, v73
	v_fmac_f32_e32 v88, v49, v74
	v_fmac_f32_e32 v88, v51, v75
	ds_read_b128 v[72:75], v39 offset:800
	s_waitcnt lgkmcnt(2)
	v_fmac_f32_e32 v88, v59, v80
	v_fmac_f32_e32 v88, v58, v81
	v_fmac_f32_e32 v88, v56, v82
	v_fmac_f32_e32 v88, v21, v83
	ds_read_b128 v[80:83], v39 offset:816
	s_waitcnt lgkmcnt(1)
	v_fmac_f32_e32 v88, v34, v72
	v_fmac_f32_e32 v88, v35, v73
	v_fma_f32 v89, v46, v76, v17
	v_fmac_f32_e32 v88, v32, v74
	v_fmac_f32_e32 v89, v48, v77
	v_fmac_f32_e32 v88, v33, v75
	v_fmac_f32_e32 v89, v50, v78
	s_waitcnt lgkmcnt(0)
	v_fmac_f32_e32 v88, v30, v80
	v_fmac_f32_e32 v89, v53, v79
	v_fmac_f32_e32 v88, v31, v81
	v_pk_mul_f32 v[74:75], v[4:5], v[82:83]
	v_fmac_f32_e32 v89, v57, v84
	ds_read_b128 v[76:79], v39 offset:864
	v_add_f32_e32 v74, v88, v74
	v_fmac_f32_e32 v89, v55, v85
	v_add_f32_e32 v74, v74, v75
	v_fmac_f32_e32 v89, v54, v86
	v_mul_f32_e64 v75, |v74|, s53
	v_fmac_f32_e32 v89, v45, v87
	ds_read_b128 v[84:87], v39 offset:880
	v_exp_f32_e32 v75, v75
	s_waitcnt lgkmcnt(1)
	v_fmac_f32_e32 v89, v28, v76
	v_fmac_f32_e32 v89, v29, v77
	v_fmac_f32_e32 v89, v6, v78
	v_add_f32_e32 v75, 1.0, v75
	v_fmac_f32_e32 v89, v7, v79
	s_waitcnt lgkmcnt(0)
	v_pk_mul_f32 v[72:73], v[2:3], v[84:85]
	v_cmp_gt_f32_e32 vcc, s54, v75
	v_add_f32_e32 v72, v89, v72
	v_add_f32_e32 v76, v72, v73
	v_cndmask_b32_e64 v77, 0, 32, vcc
	v_pk_mul_f32 v[72:73], v[0:1], v[86:87]
	v_ldexp_f32 v75, v75, v77
	v_log_f32_e32 v75, v75
	v_add_f32_e32 v72, v76, v72
	v_add_f32_e32 v72, v72, v73
	v_mul_f32_e64 v76, |v72|, s53
	v_exp_f32_e32 v76, v76
	v_min_f32_e32 v73, 0, v74
	v_mul_f32_e32 v74, 0x3f317217, v75
	v_fma_f32 v74, v75, s55, -v74
	v_fmac_f32_e32 v74, 0x3377d1cf, v75
	v_fmac_f32_e32 v74, 0x3f317217, v75
	v_cmp_lt_f32_e64 s[16:17], |v75|, s56
	v_add_f32_e32 v76, 1.0, v76
	v_min_f32_e32 v72, 0, v72
	v_cndmask_b32_e64 v74, v75, v74, s[16:17]
	v_cndmask_b32_e32 v75, 0, v44, vcc
	v_cmp_gt_f32_e32 vcc, s54, v76
	v_sub_f32_e32 v74, v74, v75
	v_sub_f32_e32 v73, v73, v74
	v_cndmask_b32_e64 v77, 0, 32, vcc
	v_ldexp_f32 v76, v76, v77
	v_log_f32_e32 v76, v76
	v_cndmask_b32_e32 v79, 0, v44, vcc
	ds_read_b128 v[86:89], v39 offset:976
	v_mul_f32_e32 v74, 0x3f317217, v76
	v_fma_f32 v74, v76, s55, -v74
	v_fmac_f32_e32 v74, 0x3377d1cf, v76
	v_fmac_f32_e32 v74, 0x3f317217, v76
	v_cmp_lt_f32_e64 s[16:17], |v76|, s56
	s_nop 1
	v_cndmask_b32_e64 v78, v76, v74, s[16:17]
	ds_read_b128 v[74:77], v39 offset:896
	v_sub_f32_e32 v82, v78, v79
	v_sub_f32_e32 v72, v72, v82
	ds_read_b128 v[82:85], v39 offset:912
	ds_read_b128 v[78:81], v39 offset:960
	s_waitcnt lgkmcnt(2)
	v_fma_f32 v90, v52, v74, v19
	v_fmac_f32_e32 v90, v47, v75
	v_fmac_f32_e32 v90, v49, v76
	v_fmac_f32_e32 v90, v51, v77
	ds_read_b128 v[74:77], v39 offset:928
	s_waitcnt lgkmcnt(2)
	v_fmac_f32_e32 v90, v59, v82
	v_fmac_f32_e32 v90, v58, v83
	v_fmac_f32_e32 v90, v56, v84
	v_fmac_f32_e32 v90, v21, v85
	ds_read_b128 v[82:85], v39 offset:944
	s_waitcnt lgkmcnt(1)
	v_fmac_f32_e32 v90, v34, v74
	v_fmac_f32_e32 v90, v35, v75
	v_fma_f32 v91, v46, v78, v17
	v_fmac_f32_e32 v90, v32, v76
	v_fmac_f32_e32 v91, v48, v79
	v_fmac_f32_e32 v90, v33, v77
	v_fmac_f32_e32 v91, v50, v80
	s_waitcnt lgkmcnt(0)
	v_fmac_f32_e32 v90, v30, v82
	v_fmac_f32_e32 v91, v53, v81
	v_fmac_f32_e32 v90, v31, v83
	v_pk_mul_f32 v[76:77], v[4:5], v[84:85]
	v_fmac_f32_e32 v91, v57, v86
	ds_read_b128 v[78:81], v39 offset:992
	v_add_f32_e32 v76, v90, v76
	v_fmac_f32_e32 v91, v55, v87
	v_add_f32_e32 v76, v76, v77
	v_fmac_f32_e32 v91, v54, v88
	v_mul_f32_e64 v77, |v76|, s53
	v_fmac_f32_e32 v91, v45, v89
	ds_read_b128 v[86:89], v39 offset:1008
	v_exp_f32_e32 v77, v77
	s_waitcnt lgkmcnt(1)
	v_fmac_f32_e32 v91, v28, v78
	v_fmac_f32_e32 v91, v29, v79
	v_fmac_f32_e32 v91, v6, v80
	v_add_f32_e32 v77, 1.0, v77
	v_fmac_f32_e32 v91, v7, v81
	s_waitcnt lgkmcnt(0)
; DI float log_sigmoid(float z) { return fminf(z, 0.f) - __logf(1.f + fexp(-fabsf(z))); }
; DI void gla_gates(const P& p, int t0, int hh, char* smem, float (&bfv)[16], float (&bbv)[16], float& totf, float& totb) {
;     ...
; #pragma unroll
;   for (int j = 0; j < 16; ++j) {
;     const float* gr = gs + (tg * 16 + j) * 32;
;     float zf = biasf, zb = biasb;
; #pragma unroll
;     for (int r = 0; r < 16; ++r) { zf += gr[r] * wf[r]; zb += gr[16 + r] * wb[r]; }
;     bfv[j] = log_sigmoid(zf) * (1.f / 16.f);
;     bbv[j] = log_sigmoid(zb) * (1.f / 16.f);
;   }
	v_pk_mul_f32 v[74:75], v[2:3], v[86:87]
	v_cmp_gt_f32_e32 vcc, s54, v77
	v_add_f32_e32 v74, v91, v74
	v_add_f32_e32 v78, v74, v75
	v_cndmask_b32_e64 v79, 0, 32, vcc
	v_pk_mul_f32 v[74:75], v[0:1], v[88:89]
	v_ldexp_f32 v77, v77, v79
	v_log_f32_e32 v77, v77
	v_add_f32_e32 v74, v78, v74
	v_add_f32_e32 v74, v74, v75
	v_mul_f32_e64 v78, |v74|, s53
	v_exp_f32_e32 v78, v78
	v_min_f32_e32 v75, 0, v76
	v_mul_f32_e32 v76, 0x3f317217, v77
	v_fma_f32 v76, v77, s55, -v76
	v_fmac_f32_e32 v76, 0x3377d1cf, v77
	v_fmac_f32_e32 v76, 0x3f317217, v77
	v_cmp_lt_f32_e64 s[16:17], |v77|, s56
	v_add_f32_e32 v78, 1.0, v78
	v_min_f32_e32 v74, 0, v74
	v_cndmask_b32_e64 v76, v77, v76, s[16:17]
	v_cndmask_b32_e32 v77, 0, v44, vcc
	v_cmp_gt_f32_e32 vcc, s54, v78
	v_sub_f32_e32 v76, v76, v77
	v_sub_f32_e32 v75, v75, v76
	v_cndmask_b32_e64 v79, 0, 32, vcc
	v_ldexp_f32 v78, v78, v79
	v_log_f32_e32 v78, v78
	v_cndmask_b32_e32 v81, 0, v44, vcc
	ds_read_b128 v[88:91], v39 offset:1104
	v_mul_f32_e32 v76, 0x3f317217, v78
	v_fma_f32 v76, v78, s55, -v76
	v_fmac_f32_e32 v76, 0x3377d1cf, v78
	v_fmac_f32_e32 v76, 0x3f317217, v78
	v_cmp_lt_f32_e64 s[16:17], |v78|, s56
	s_nop 1
	v_cndmask_b32_e64 v80, v78, v76, s[16:17]
	ds_read_b128 v[76:79], v39 offset:1024
	v_sub_f32_e32 v84, v80, v81
	v_sub_f32_e32 v74, v74, v84
	ds_read_b128 v[84:87], v39 offset:1040
	ds_read_b128 v[80:83], v39 offset:1088
	s_waitcnt lgkmcnt(2)
	v_fma_f32 v92, v52, v76, v19
	v_fmac_f32_e32 v92, v47, v77
	v_fmac_f32_e32 v92, v49, v78
	v_fmac_f32_e32 v92, v51, v79
	ds_read_b128 v[76:79], v39 offset:1056
	s_waitcnt lgkmcnt(2)
	v_fmac_f32_e32 v92, v59, v84
	v_fmac_f32_e32 v92, v58, v85
	v_fmac_f32_e32 v92, v56, v86
	v_fmac_f32_e32 v92, v21, v87
	ds_read_b128 v[84:87], v39 offset:1072
	s_waitcnt lgkmcnt(1)
	v_fmac_f32_e32 v92, v34, v76
	v_fmac_f32_e32 v92, v35, v77
	v_fma_f32 v93, v46, v80, v17
	v_fmac_f32_e32 v92, v32, v78
	v_fmac_f32_e32 v93, v48, v81
	v_fmac_f32_e32 v92, v33, v79
	v_fmac_f32_e32 v93, v50, v82
	s_waitcnt lgkmcnt(0)
	v_fmac_f32_e32 v92, v30, v84
	v_fmac_f32_e32 v93, v53, v83
	v_fmac_f32_e32 v92, v31, v85
	v_pk_mul_f32 v[78:79], v[4:5], v[86:87]
	v_fmac_f32_e32 v93, v57, v88
	ds_read_b128 v[80:83], v39 offset:1120
	v_add_f32_e32 v78, v92, v78
	v_fmac_f32_e32 v93, v55, v89
	v_add_f32_e32 v78, v78, v79
	v_fmac_f32_e32 v93, v54, v90
	v_mul_f32_e64 v79, |v78|, s53
	v_fmac_f32_e32 v93, v45, v91
	ds_read_b128 v[88:91], v39 offset:1136
	v_exp_f32_e32 v79, v79
	s_waitcnt lgkmcnt(1)
	v_fmac_f32_e32 v93, v28, v80
	v_fmac_f32_e32 v93, v29, v81
	v_fmac_f32_e32 v93, v6, v82
	v_add_f32_e32 v79, 1.0, v79
	v_fmac_f32_e32 v93, v7, v83
	s_waitcnt lgkmcnt(0)
	v_pk_mul_f32 v[76:77], v[2:3], v[88:89]
	v_cmp_gt_f32_e32 vcc, s54, v79
	v_add_f32_e32 v76, v93, v76
	v_add_f32_e32 v80, v76, v77
	v_cndmask_b32_e64 v81, 0, 32, vcc
	v_pk_mul_f32 v[76:77], v[0:1], v[90:91]
	v_ldexp_f32 v79, v79, v81
	v_log_f32_e32 v79, v79
	v_add_f32_e32 v76, v80, v76
	v_add_f32_e32 v76, v76, v77
	v_mul_f32_e64 v80, |v76|, s53
	v_exp_f32_e32 v80, v80
	v_min_f32_e32 v77, 0, v78
	v_mul_f32_e32 v78, 0x3f317217, v79
	v_fma_f32 v78, v79, s55, -v78
	v_fmac_f32_e32 v78, 0x3377d1cf, v79
	v_fmac_f32_e32 v78, 0x3f317217, v79
	v_cmp_lt_f32_e64 s[16:17], |v79|, s56
	v_add_f32_e32 v80, 1.0, v80
	v_min_f32_e32 v76, 0, v76
	v_cndmask_b32_e64 v78, v79, v78, s[16:17]
	v_cndmask_b32_e32 v79, 0, v44, vcc
	v_cmp_gt_f32_e32 vcc, s54, v80
	v_sub_f32_e32 v78, v78, v79
	v_sub_f32_e32 v77, v77, v78
	v_cndmask_b32_e64 v81, 0, 32, vcc
	v_ldexp_f32 v80, v80, v81
	v_log_f32_e32 v80, v80
	v_cndmask_b32_e32 v83, 0, v44, vcc
	ds_read_b128 v[90:93], v39 offset:1232
	v_mul_f32_e32 v78, 0x3f317217, v80
	v_fma_f32 v78, v80, s55, -v78
	v_fmac_f32_e32 v78, 0x3377d1cf, v80
	v_fmac_f32_e32 v78, 0x3f317217, v80
	v_cmp_lt_f32_e64 s[16:17], |v80|, s56
	s_nop 1
	v_cndmask_b32_e64 v82, v80, v78, s[16:17]
	ds_read_b128 v[78:81], v39 offset:1152
	v_sub_f32_e32 v86, v82, v83
	v_sub_f32_e32 v76, v76, v86
	ds_read_b128 v[86:89], v39 offset:1168
	ds_read_b128 v[82:85], v39 offset:1216
	s_waitcnt lgkmcnt(2)
	v_fma_f32 v94, v52, v78, v19
	v_fmac_f32_e32 v94, v47, v79
	v_fmac_f32_e32 v94, v49, v80
	v_fmac_f32_e32 v94, v51, v81
	ds_read_b128 v[78:81], v39 offset:1184
	s_waitcnt lgkmcnt(2)
	v_fmac_f32_e32 v94, v59, v86
	v_fmac_f32_e32 v94, v58, v87
	v_fmac_f32_e32 v94, v56, v88
	v_fmac_f32_e32 v94, v21, v89
	ds_read_b128 v[86:89], v39 offset:1200
	s_waitcnt lgkmcnt(1)
	v_fmac_f32_e32 v94, v34, v78
	v_fmac_f32_e32 v94, v35, v79
	v_fma_f32 v95, v46, v82, v17
	v_fmac_f32_e32 v94, v32, v80
	v_fmac_f32_e32 v95, v48, v83
	v_fmac_f32_e32 v94, v33, v81
	v_fmac_f32_e32 v95, v50, v84
	s_waitcnt lgkmcnt(0)
	v_fmac_f32_e32 v94, v30, v86
	v_fmac_f32_e32 v95, v53, v85
	v_fmac_f32_e32 v94, v31, v87
	v_pk_mul_f32 v[80:81], v[4:5], v[88:89]
	v_fmac_f32_e32 v95, v57, v90
	ds_read_b128 v[82:85], v39 offset:1248
	v_add_f32_e32 v80, v94, v80
	v_fmac_f32_e32 v95, v55, v91
	v_add_f32_e32 v80, v80, v81
	v_fmac_f32_e32 v95, v54, v92
	v_mul_f32_e64 v81, |v80|, s53
	v_fmac_f32_e32 v95, v45, v93
	ds_read_b128 v[90:93], v39 offset:1264
	v_exp_f32_e32 v81, v81
	s_waitcnt lgkmcnt(1)
	v_fmac_f32_e32 v95, v28, v82
	v_fmac_f32_e32 v95, v29, v83
	v_fmac_f32_e32 v95, v6, v84
	v_add_f32_e32 v81, 1.0, v81
	v_fmac_f32_e32 v95, v7, v85
	s_waitcnt lgkmcnt(0)
; DI float log_sigmoid(float z) { return fminf(z, 0.f) - __logf(1.f + fexp(-fabsf(z))); }
; DI void gla_gates(const P& p, int t0, int hh, char* smem, float (&bfv)[16], float (&bbv)[16], float& totf, float& totb) {
;     ...
; #pragma unroll
;   for (int j = 0; j < 16; ++j) {
;     const float* gr = gs + (tg * 16 + j) * 32;
;     float zf = biasf, zb = biasb;
; #pragma unroll
;     for (int r = 0; r < 16; ++r) { zf += gr[r] * wf[r]; zb += gr[16 + r] * wb[r]; }
;     bfv[j] = log_sigmoid(zf) * (1.f / 16.f);
;     bbv[j] = log_sigmoid(zb) * (1.f / 16.f);
;   }
	v_pk_mul_f32 v[78:79], v[2:3], v[90:91]
	v_cmp_gt_f32_e32 vcc, s54, v81
	v_add_f32_e32 v78, v95, v78
	v_add_f32_e32 v82, v78, v79
	v_cndmask_b32_e64 v83, 0, 32, vcc
	v_pk_mul_f32 v[78:79], v[0:1], v[92:93]
	v_ldexp_f32 v81, v81, v83
	v_log_f32_e32 v81, v81
	v_add_f32_e32 v78, v82, v78
	v_add_f32_e32 v78, v78, v79
	v_mul_f32_e64 v82, |v78|, s53
	v_exp_f32_e32 v82, v82
	v_min_f32_e32 v79, 0, v80
	v_mul_f32_e32 v80, 0x3f317217, v81
	v_fma_f32 v80, v81, s55, -v80
	v_fmac_f32_e32 v80, 0x3377d1cf, v81
	v_fmac_f32_e32 v80, 0x3f317217, v81
	v_cmp_lt_f32_e64 s[16:17], |v81|, s56
	v_add_f32_e32 v82, 1.0, v82
	v_min_f32_e32 v78, 0, v78
	v_cndmask_b32_e64 v80, v81, v80, s[16:17]
	v_cndmask_b32_e32 v81, 0, v44, vcc
	v_cmp_gt_f32_e32 vcc, s54, v82
	v_sub_f32_e32 v80, v80, v81
	v_sub_f32_e32 v79, v79, v80
	v_cndmask_b32_e64 v83, 0, 32, vcc
	v_ldexp_f32 v82, v82, v83
	v_log_f32_e32 v82, v82
	v_cndmask_b32_e32 v85, 0, v44, vcc
	ds_read_b128 v[92:95], v39 offset:1360
	v_mul_f32_e32 v80, 0x3f317217, v82
	v_fma_f32 v80, v82, s55, -v80
	v_fmac_f32_e32 v80, 0x3377d1cf, v82
	v_fmac_f32_e32 v80, 0x3f317217, v82
	v_cmp_lt_f32_e64 s[16:17], |v82|, s56
	s_nop 1
	v_cndmask_b32_e64 v84, v82, v80, s[16:17]
	ds_read_b128 v[80:83], v39 offset:1280
	v_sub_f32_e32 v88, v84, v85
	v_sub_f32_e32 v78, v78, v88
	ds_read_b128 v[88:91], v39 offset:1296
	ds_read_b128 v[84:87], v39 offset:1344
	s_waitcnt lgkmcnt(2)
	v_fma_f32 v96, v52, v80, v19
	v_fmac_f32_e32 v96, v47, v81
	v_fmac_f32_e32 v96, v49, v82
	v_fmac_f32_e32 v96, v51, v83
	ds_read_b128 v[80:83], v39 offset:1312
	s_waitcnt lgkmcnt(2)
	v_fmac_f32_e32 v96, v59, v88
	v_fmac_f32_e32 v96, v58, v89
	v_fmac_f32_e32 v96, v56, v90
	v_fmac_f32_e32 v96, v21, v91
	ds_read_b128 v[88:91], v39 offset:1328
	s_waitcnt lgkmcnt(1)
	v_fmac_f32_e32 v96, v34, v80
	v_fmac_f32_e32 v96, v35, v81
	v_fma_f32 v97, v46, v84, v17
	v_fmac_f32_e32 v96, v32, v82
	v_fmac_f32_e32 v97, v48, v85
	v_fmac_f32_e32 v96, v33, v83
	v_fmac_f32_e32 v97, v50, v86
	s_waitcnt lgkmcnt(0)
	v_fmac_f32_e32 v96, v30, v88
	v_fmac_f32_e32 v97, v53, v87
	v_fmac_f32_e32 v96, v31, v89
	v_pk_mul_f32 v[82:83], v[4:5], v[90:91]
	v_fmac_f32_e32 v97, v57, v92
	ds_read_b128 v[84:87], v39 offset:1376
	v_add_f32_e32 v82, v96, v82
	v_fmac_f32_e32 v97, v55, v93
	v_add_f32_e32 v82, v82, v83
	v_fmac_f32_e32 v97, v54, v94
	v_mul_f32_e64 v83, |v82|, s53
	v_fmac_f32_e32 v97, v45, v95
	ds_read_b128 v[92:95], v39 offset:1392
	v_exp_f32_e32 v83, v83
	s_waitcnt lgkmcnt(1)
	v_fmac_f32_e32 v97, v28, v84
	v_fmac_f32_e32 v97, v29, v85
	v_fmac_f32_e32 v97, v6, v86
	v_add_f32_e32 v83, 1.0, v83
	v_fmac_f32_e32 v97, v7, v87
	s_waitcnt lgkmcnt(0)
	v_pk_mul_f32 v[80:81], v[2:3], v[92:93]
	v_cmp_gt_f32_e32 vcc, s54, v83
	v_add_f32_e32 v80, v97, v80
	v_add_f32_e32 v84, v80, v81
	v_cndmask_b32_e64 v85, 0, 32, vcc
	v_pk_mul_f32 v[80:81], v[0:1], v[94:95]
	v_ldexp_f32 v83, v83, v85
	v_log_f32_e32 v83, v83
	v_add_f32_e32 v80, v84, v80
	v_add_f32_e32 v80, v80, v81
	v_mul_f32_e64 v84, |v80|, s53
	v_exp_f32_e32 v84, v84
	v_min_f32_e32 v81, 0, v82
	v_mul_f32_e32 v82, 0x3f317217, v83
	v_fma_f32 v82, v83, s55, -v82
	v_fmac_f32_e32 v82, 0x3377d1cf, v83
	v_fmac_f32_e32 v82, 0x3f317217, v83
	v_cmp_lt_f32_e64 s[16:17], |v83|, s56
	v_add_f32_e32 v84, 1.0, v84
	v_min_f32_e32 v80, 0, v80
	v_cndmask_b32_e64 v82, v83, v82, s[16:17]
	v_cndmask_b32_e32 v83, 0, v44, vcc
	v_cmp_gt_f32_e32 vcc, s54, v84
	v_sub_f32_e32 v82, v82, v83
	v_sub_f32_e32 v81, v81, v82
	v_cndmask_b32_e64 v85, 0, 32, vcc
	v_ldexp_f32 v84, v84, v85
	v_log_f32_e32 v84, v84
	v_cndmask_b32_e32 v87, 0, v44, vcc
	ds_read_b128 v[94:97], v39 offset:1488
	v_mul_f32_e32 v82, 0x3f317217, v84
	v_fma_f32 v82, v84, s55, -v82
	v_fmac_f32_e32 v82, 0x3377d1cf, v84
	v_fmac_f32_e32 v82, 0x3f317217, v84
	v_cmp_lt_f32_e64 s[16:17], |v84|, s56
	s_nop 1
	v_cndmask_b32_e64 v86, v84, v82, s[16:17]
	ds_read_b128 v[82:85], v39 offset:1408
	v_sub_f32_e32 v90, v86, v87
	v_sub_f32_e32 v80, v80, v90
	ds_read_b128 v[90:93], v39 offset:1424
	ds_read_b128 v[86:89], v39 offset:1472
	s_waitcnt lgkmcnt(2)
	v_fma_f32 v98, v52, v82, v19
	v_fmac_f32_e32 v98, v47, v83
	v_fmac_f32_e32 v98, v49, v84
	v_fmac_f32_e32 v98, v51, v85
	s_waitcnt lgkmcnt(1)
	v_fmac_f32_e32 v98, v59, v90
	ds_read_b128 v[82:85], v39 offset:1440
	v_fmac_f32_e32 v98, v58, v91
	s_waitcnt lgkmcnt(1)
	v_fma_f32 v99, v46, v86, v17
	v_fmac_f32_e32 v98, v56, v92
	v_fmac_f32_e32 v99, v48, v87
	v_fmac_f32_e32 v98, v21, v93
	ds_read_b128 v[90:93], v39 offset:1456
	v_fmac_f32_e32 v99, v50, v88
	v_fmac_f32_e32 v99, v53, v89
	ds_read_b128 v[86:89], v39 offset:1504
	s_waitcnt lgkmcnt(2)
	v_fmac_f32_e32 v98, v34, v82
	v_fmac_f32_e32 v99, v57, v94
	v_fmac_f32_e32 v98, v35, v83
	v_fmac_f32_e32 v99, v55, v95
	v_fmac_f32_e32 v98, v32, v84
	v_fmac_f32_e32 v99, v54, v96
	v_fmac_f32_e32 v98, v33, v85
	s_waitcnt lgkmcnt(1)
	v_pk_mul_f32 v[82:83], v[30:31], v[90:91]
	v_fmac_f32_e32 v99, v45, v97
	v_add_f32_e32 v82, v98, v82
	ds_read_b128 v[94:97], v39 offset:1520
	s_waitcnt lgkmcnt(1)
	v_fmac_f32_e32 v99, v28, v86
	v_add_f32_e32 v86, v82, v83
	v_pk_mul_f32 v[84:85], v[4:5], v[92:93]
	v_fmac_f32_e32 v99, v29, v87
	v_add_f32_e32 v84, v86, v84
	v_add_f32_e32 v84, v84, v85
	v_mul_f32_e64 v85, |v84|, s53
	v_exp_f32_e32 v85, v85
	v_fmac_f32_e32 v99, v6, v88
	v_fmac_f32_e32 v99, v7, v89
	s_waitcnt lgkmcnt(0)
; DI float log_sigmoid(float z) { return fminf(z, 0.f) - __logf(1.f + fexp(-fabsf(z))); }
; DI void gla_gates(const P& p, int t0, int hh, char* smem, float (&bfv)[16], float (&bbv)[16], float& totf, float& totb) {
;     ...
; #pragma unroll
;   for (int j = 0; j < 16; ++j) {
;     const float* gr = gs + (tg * 16 + j) * 32;
;     float zf = biasf, zb = biasb;
; #pragma unroll
;     for (int r = 0; r < 16; ++r) { zf += gr[r] * wf[r]; zb += gr[16 + r] * wb[r]; }
;     bfv[j] = log_sigmoid(zf) * (1.f / 16.f);
;     bbv[j] = log_sigmoid(zb) * (1.f / 16.f);
;   }
	v_pk_mul_f32 v[82:83], v[2:3], v[94:95]
	v_add_f32_e32 v85, 1.0, v85
	v_cmp_gt_f32_e32 vcc, s54, v85
	v_add_f32_e32 v82, v99, v82
	v_add_f32_e32 v86, v82, v83
	v_cndmask_b32_e64 v87, 0, 32, vcc
	v_pk_mul_f32 v[82:83], v[0:1], v[96:97]
	v_ldexp_f32 v85, v85, v87
	v_log_f32_e32 v85, v85
	v_add_f32_e32 v82, v86, v82
	v_add_f32_e32 v82, v82, v83
	v_mul_f32_e64 v86, |v82|, s53
	v_exp_f32_e32 v86, v86
	v_min_f32_e32 v83, 0, v84
	v_mul_f32_e32 v84, 0x3f317217, v85
	v_fma_f32 v84, v85, s55, -v84
	v_fmac_f32_e32 v84, 0x3377d1cf, v85
	v_fmac_f32_e32 v84, 0x3f317217, v85
	v_cmp_lt_f32_e64 s[16:17], |v85|, s56
	v_add_f32_e32 v86, 1.0, v86
	v_min_f32_e32 v82, 0, v82
	v_cndmask_b32_e64 v84, v85, v84, s[16:17]
	v_cndmask_b32_e32 v85, 0, v44, vcc
	v_cmp_gt_f32_e32 vcc, s54, v86
	v_sub_f32_e32 v84, v84, v85
	v_sub_f32_e32 v83, v83, v84
	v_cndmask_b32_e64 v87, 0, 32, vcc
	v_ldexp_f32 v86, v86, v87
	v_log_f32_e32 v86, v86
	v_cndmask_b32_e32 v89, 0, v44, vcc
	ds_read_b128 v[96:99], v39 offset:1616
	v_mul_f32_e32 v84, 0x3f317217, v86
	v_fma_f32 v84, v86, s55, -v84
	v_fmac_f32_e32 v84, 0x3377d1cf, v86
	v_fmac_f32_e32 v84, 0x3f317217, v86
	v_cmp_lt_f32_e64 s[16:17], |v86|, s56
	s_nop 1
	v_cndmask_b32_e64 v88, v86, v84, s[16:17]
	ds_read_b128 v[84:87], v39 offset:1536
	v_sub_f32_e32 v92, v88, v89
	v_sub_f32_e32 v82, v82, v92
	ds_read_b128 v[92:95], v39 offset:1552
	ds_read_b128 v[88:91], v39 offset:1600
	s_waitcnt lgkmcnt(2)
	v_fma_f32 v100, v52, v84, v19
	v_fmac_f32_e32 v100, v47, v85
	v_fmac_f32_e32 v100, v49, v86
	v_fmac_f32_e32 v100, v51, v87
	s_waitcnt lgkmcnt(1)
	v_fmac_f32_e32 v100, v59, v92
	ds_read_b128 v[84:87], v39 offset:1568
	v_fmac_f32_e32 v100, v58, v93
	s_waitcnt lgkmcnt(1)
	v_fma_f32 v101, v46, v88, v17
	v_fmac_f32_e32 v100, v56, v94
	v_fmac_f32_e32 v101, v48, v89
	v_fmac_f32_e32 v100, v21, v95
	ds_read_b128 v[92:95], v39 offset:1584
	v_fmac_f32_e32 v101, v50, v90
	v_fmac_f32_e32 v101, v53, v91
	ds_read_b128 v[88:91], v39 offset:1632
	s_waitcnt lgkmcnt(2)
	v_fmac_f32_e32 v100, v34, v84
	v_fmac_f32_e32 v101, v57, v96
	v_fmac_f32_e32 v100, v35, v85
	v_fmac_f32_e32 v101, v55, v97
	v_fmac_f32_e32 v100, v32, v86
	v_fmac_f32_e32 v101, v54, v98
	v_fmac_f32_e32 v100, v33, v87
	s_waitcnt lgkmcnt(1)
	v_pk_mul_f32 v[84:85], v[30:31], v[92:93]
	v_fmac_f32_e32 v101, v45, v99
	v_add_f32_e32 v84, v100, v84
	ds_read_b128 v[96:99], v39 offset:1648
	s_waitcnt lgkmcnt(1)
	v_fmac_f32_e32 v101, v28, v88
	v_add_f32_e32 v88, v84, v85
	v_pk_mul_f32 v[86:87], v[4:5], v[94:95]
	v_fmac_f32_e32 v101, v29, v89
	v_add_f32_e32 v86, v88, v86
	v_add_f32_e32 v86, v86, v87
	v_mul_f32_e64 v87, |v86|, s53
	v_exp_f32_e32 v87, v87
	v_fmac_f32_e32 v101, v6, v90
	v_fmac_f32_e32 v101, v7, v91
	s_waitcnt lgkmcnt(0)
	v_pk_mul_f32 v[84:85], v[2:3], v[96:97]
	v_add_f32_e32 v87, 1.0, v87
	v_cmp_gt_f32_e32 vcc, s54, v87
	v_add_f32_e32 v84, v101, v84
	v_add_f32_e32 v88, v84, v85
	v_cndmask_b32_e64 v89, 0, 32, vcc
	v_pk_mul_f32 v[84:85], v[0:1], v[98:99]
	v_ldexp_f32 v87, v87, v89
	v_log_f32_e32 v87, v87
	v_add_f32_e32 v84, v88, v84
	v_add_f32_e32 v84, v84, v85
	v_mul_f32_e64 v88, |v84|, s53
	v_exp_f32_e32 v88, v88
	v_min_f32_e32 v85, 0, v86
	v_mul_f32_e32 v86, 0x3f317217, v87
	v_fma_f32 v86, v87, s55, -v86
	v_fmac_f32_e32 v86, 0x3377d1cf, v87
	v_fmac_f32_e32 v86, 0x3f317217, v87
	v_cmp_lt_f32_e64 s[16:17], |v87|, s56
	v_add_f32_e32 v88, 1.0, v88
	v_min_f32_e32 v92, 0, v84
	v_cndmask_b32_e64 v86, v87, v86, s[16:17]
	v_cndmask_b32_e32 v87, 0, v44, vcc
	v_cmp_gt_f32_e32 vcc, s54, v88
	v_sub_f32_e32 v86, v86, v87
	v_sub_f32_e32 v100, v85, v86
	v_cndmask_b32_e64 v89, 0, 32, vcc
	v_ldexp_f32 v88, v88, v89
	v_log_f32_e32 v88, v88
	v_cndmask_b32_e32 v89, 0, v44, vcc
	ds_read_b128 v[96:99], v39 offset:1744
	v_mul_f32_e32 v84, 0x3f317217, v88
	v_fma_f32 v84, v88, s55, -v84
	v_fmac_f32_e32 v84, 0x3377d1cf, v88
	v_fmac_f32_e32 v84, 0x3f317217, v88
	v_cmp_lt_f32_e64 s[16:17], |v88|, s56
	s_nop 1
	v_cndmask_b32_e64 v88, v88, v84, s[16:17]
	ds_read_b128 v[84:87], v39 offset:1664
	v_sub_f32_e32 v93, v88, v89
	v_sub_f32_e32 v101, v92, v93
	ds_read_b128 v[92:95], v39 offset:1680
	ds_read_b128 v[88:91], v39 offset:1728
	s_waitcnt lgkmcnt(2)
	v_fma_f32 v102, v52, v84, v19
	v_fmac_f32_e32 v102, v47, v85
	v_fmac_f32_e32 v102, v49, v86
	v_fmac_f32_e32 v102, v51, v87
	s_waitcnt lgkmcnt(1)
	v_fmac_f32_e32 v102, v59, v92
	ds_read_b128 v[84:87], v39 offset:1696
	v_fmac_f32_e32 v102, v58, v93
	s_waitcnt lgkmcnt(1)
	v_fma_f32 v103, v46, v88, v17
	v_fmac_f32_e32 v102, v56, v94
	v_fmac_f32_e32 v103, v48, v89
	v_fmac_f32_e32 v102, v21, v95
	ds_read_b128 v[92:95], v39 offset:1712
	v_fmac_f32_e32 v103, v50, v90
	v_fmac_f32_e32 v103, v53, v91
	ds_read_b128 v[88:91], v39 offset:1760
	s_waitcnt lgkmcnt(2)
	v_fmac_f32_e32 v102, v34, v84
	v_fmac_f32_e32 v103, v57, v96
	v_fmac_f32_e32 v102, v35, v85
	v_pk_mul_f32 v[84:85], v[32:33], v[86:87]
	v_fmac_f32_e32 v103, v55, v97
	v_add_f32_e32 v84, v102, v84
	v_fmac_f32_e32 v103, v54, v98
	v_add_f32_e32 v86, v84, v85
	s_waitcnt lgkmcnt(1)
	v_pk_mul_f32 v[84:85], v[30:31], v[92:93]
	v_fmac_f32_e32 v103, v45, v99
	v_add_f32_e32 v84, v86, v84
	ds_read_b128 v[96:99], v39 offset:1776
	s_waitcnt lgkmcnt(1)
	v_fmac_f32_e32 v103, v28, v88
	v_add_f32_e32 v88, v84, v85
	v_pk_mul_f32 v[86:87], v[4:5], v[94:95]
	v_fmac_f32_e32 v103, v29, v89
	v_add_f32_e32 v86, v88, v86
	v_add_f32_e32 v86, v86, v87
	v_mul_f32_e64 v87, |v86|, s53
	v_exp_f32_e32 v87, v87
	v_fmac_f32_e32 v103, v6, v90
	v_fmac_f32_e32 v103, v7, v91
	s_waitcnt lgkmcnt(0)
; DI float log_sigmoid(float z) { return fminf(z, 0.f) - __logf(1.f + fexp(-fabsf(z))); }
; DI void gla_gates(const P& p, int t0, int hh, char* smem, float (&bfv)[16], float (&bbv)[16], float& totf, float& totb) {
;     ...
; #pragma unroll
;   for (int j = 0; j < 16; ++j) {
;     const float* gr = gs + (tg * 16 + j) * 32;
;     float zf = biasf, zb = biasb;
; #pragma unroll
;     for (int r = 0; r < 16; ++r) { zf += gr[r] * wf[r]; zb += gr[16 + r] * wb[r]; }
;     bfv[j] = log_sigmoid(zf) * (1.f / 16.f);
;     bbv[j] = log_sigmoid(zb) * (1.f / 16.f);
;   }
	v_pk_mul_f32 v[84:85], v[2:3], v[96:97]
	v_add_f32_e32 v87, 1.0, v87
	v_cmp_gt_f32_e32 vcc, s54, v87
	v_add_f32_e32 v84, v103, v84
	v_add_f32_e32 v88, v84, v85
	v_cndmask_b32_e64 v89, 0, 32, vcc
	v_pk_mul_f32 v[84:85], v[0:1], v[98:99]
	v_ldexp_f32 v87, v87, v89
	v_log_f32_e32 v87, v87
	v_add_f32_e32 v84, v88, v84
	v_add_f32_e32 v84, v84, v85
	v_mul_f32_e64 v88, |v84|, s53
	v_exp_f32_e32 v88, v88
	v_min_f32_e32 v85, 0, v86
	v_mul_f32_e32 v86, 0x3f317217, v87
	v_fma_f32 v86, v87, s55, -v86
	v_fmac_f32_e32 v86, 0x3377d1cf, v87
	v_fmac_f32_e32 v86, 0x3f317217, v87
	v_cmp_lt_f32_e64 s[16:17], |v87|, s56
	v_add_f32_e32 v88, 1.0, v88
	v_min_f32_e32 v92, 0, v84
	v_cndmask_b32_e64 v86, v87, v86, s[16:17]
	v_cndmask_b32_e32 v87, 0, v44, vcc
	v_cmp_gt_f32_e32 vcc, s54, v88
	v_sub_f32_e32 v86, v86, v87
	v_sub_f32_e32 v102, v85, v86
	v_cndmask_b32_e64 v89, 0, 32, vcc
	v_ldexp_f32 v88, v88, v89
	v_log_f32_e32 v88, v88
	v_cndmask_b32_e32 v89, 0, v44, vcc
	ds_read_b128 v[96:99], v39 offset:1872
	v_mul_f32_e32 v84, 0x3f317217, v88
	v_fma_f32 v84, v88, s55, -v84
	v_fmac_f32_e32 v84, 0x3377d1cf, v88
	v_fmac_f32_e32 v84, 0x3f317217, v88
	v_cmp_lt_f32_e64 s[16:17], |v88|, s56
	s_nop 1
	v_cndmask_b32_e64 v88, v88, v84, s[16:17]
	ds_read_b128 v[84:87], v39 offset:1792
	v_sub_f32_e32 v93, v88, v89
	v_sub_f32_e32 v103, v92, v93
	ds_read_b128 v[92:95], v39 offset:1808
	ds_read_b128 v[88:91], v39 offset:1856
	s_waitcnt lgkmcnt(2)
	v_fma_f32 v104, v52, v84, v19
	v_fmac_f32_e32 v104, v47, v85
	v_fmac_f32_e32 v104, v49, v86
	v_fmac_f32_e32 v104, v51, v87
	s_waitcnt lgkmcnt(1)
	v_fmac_f32_e32 v104, v59, v92
	ds_read_b128 v[84:87], v39 offset:1824
	v_fmac_f32_e32 v104, v58, v93
	s_waitcnt lgkmcnt(1)
	v_fma_f32 v105, v46, v88, v17
	v_fmac_f32_e32 v104, v56, v94
	v_fmac_f32_e32 v105, v48, v89
	v_fmac_f32_e32 v104, v21, v95
	ds_read_b128 v[92:95], v39 offset:1840
	v_fmac_f32_e32 v105, v50, v90
	v_fmac_f32_e32 v105, v53, v91
	ds_read_b128 v[88:91], v39 offset:1888
	s_waitcnt lgkmcnt(2)
	v_fmac_f32_e32 v104, v34, v84
	v_fmac_f32_e32 v105, v57, v96
	v_fmac_f32_e32 v104, v35, v85
	v_pk_mul_f32 v[84:85], v[32:33], v[86:87]
	v_fmac_f32_e32 v105, v55, v97
	v_add_f32_e32 v84, v104, v84
	v_fmac_f32_e32 v105, v54, v98
	v_add_f32_e32 v86, v84, v85
	s_waitcnt lgkmcnt(1)
	v_pk_mul_f32 v[84:85], v[30:31], v[92:93]
	v_fmac_f32_e32 v105, v45, v99
	v_add_f32_e32 v84, v86, v84
	ds_read_b128 v[96:99], v39 offset:1904
	s_waitcnt lgkmcnt(1)
	v_fmac_f32_e32 v105, v28, v88
	v_add_f32_e32 v88, v84, v85
	v_pk_mul_f32 v[86:87], v[4:5], v[94:95]
	v_fmac_f32_e32 v105, v29, v89
	v_add_f32_e32 v86, v88, v86
	v_add_f32_e32 v86, v86, v87
	v_mul_f32_e64 v87, |v86|, s53
	v_exp_f32_e32 v87, v87
	v_fmac_f32_e32 v105, v6, v90
	v_fmac_f32_e32 v105, v7, v91
	s_waitcnt lgkmcnt(0)
	v_pk_mul_f32 v[84:85], v[2:3], v[96:97]
	v_add_f32_e32 v87, 1.0, v87
	v_cmp_gt_f32_e32 vcc, s54, v87
	v_add_f32_e32 v84, v105, v84
	v_add_f32_e32 v88, v84, v85
	v_cndmask_b32_e64 v89, 0, 32, vcc
	v_pk_mul_f32 v[84:85], v[0:1], v[98:99]
	v_ldexp_f32 v87, v87, v89
	v_log_f32_e32 v87, v87
	v_add_f32_e32 v84, v88, v84
	v_add_f32_e32 v84, v84, v85
	v_mul_f32_e64 v88, |v84|, s53
	v_exp_f32_e32 v88, v88
	v_min_f32_e32 v85, 0, v86
	v_mul_f32_e32 v86, 0x3f317217, v87
	v_fma_f32 v86, v87, s55, -v86
	v_fmac_f32_e32 v86, 0x3377d1cf, v87
	v_fmac_f32_e32 v86, 0x3f317217, v87
	v_cmp_lt_f32_e64 s[16:17], |v87|, s56
	v_add_f32_e32 v88, 1.0, v88
	v_min_f32_e32 v92, 0, v84
	v_cndmask_b32_e64 v86, v87, v86, s[16:17]
	v_cndmask_b32_e32 v87, 0, v44, vcc
	v_cmp_gt_f32_e32 vcc, s54, v88
	v_sub_f32_e32 v86, v86, v87
	v_sub_f32_e32 v104, v85, v86
	v_cndmask_b32_e64 v89, 0, 32, vcc
	v_ldexp_f32 v88, v88, v89
	v_log_f32_e32 v88, v88
	v_cndmask_b32_e32 v89, 0, v44, vcc
	ds_read_b128 v[96:99], v39 offset:2000
	v_mul_f32_e32 v84, 0x3f317217, v88
	v_fma_f32 v84, v88, s55, -v84
	v_fmac_f32_e32 v84, 0x3377d1cf, v88
	v_fmac_f32_e32 v84, 0x3f317217, v88
	v_cmp_lt_f32_e64 s[16:17], |v88|, s56
	s_nop 1
	v_cndmask_b32_e64 v88, v88, v84, s[16:17]
	ds_read_b128 v[84:87], v39 offset:1920
	v_sub_f32_e32 v93, v88, v89
	ds_read_b128 v[88:91], v39 offset:1984
	v_sub_f32_e32 v105, v92, v93
	ds_read_b128 v[92:95], v39 offset:1936
	s_waitcnt lgkmcnt(2)
	v_fmac_f32_e32 v19, v52, v84
	v_fmac_f32_e32 v19, v47, v85
	s_waitcnt lgkmcnt(1)
	v_fmac_f32_e32 v17, v46, v88
	v_fmac_f32_e32 v17, v48, v89
	v_fmac_f32_e32 v19, v49, v86
	v_fmac_f32_e32 v17, v50, v90
	v_fmac_f32_e32 v19, v51, v87
	v_fmac_f32_e32 v17, v53, v91
	s_waitcnt lgkmcnt(0)
	v_fmac_f32_e32 v19, v59, v92
	ds_read_b128 v[46:49], v39 offset:1952
	v_fmac_f32_e32 v17, v57, v96
	v_fmac_f32_e32 v19, v58, v93
	v_fmac_f32_e32 v17, v55, v97
	v_fmac_f32_e32 v19, v56, v94
	v_fmac_f32_e32 v17, v54, v98
	ds_read_b128 v[50:53], v39 offset:2016
	ds_read_b128 v[54:57], v39 offset:1968
	v_fmac_f32_e32 v19, v21, v95
	v_fmac_f32_e32 v17, v45, v99
	s_waitcnt lgkmcnt(2)
	v_pk_mul_f32 v[34:35], v[34:35], v[46:47]
	s_waitcnt lgkmcnt(1)
	v_pk_mul_f32 v[28:29], v[28:29], v[50:51]
	v_add_f32_e32 v19, v19, v34
	v_add_f32_e32 v17, v17, v28
	v_add_f32_e32 v19, v19, v35
	v_add_f32_e32 v17, v17, v29
	v_pk_mul_f32 v[28:29], v[32:33], v[48:49]
	v_pk_mul_f32 v[6:7], v[6:7], v[52:53]
	v_add_f32_e32 v19, v19, v28
	v_add_f32_e32 v6, v17, v6
	v_add_f32_e32 v19, v19, v29
	v_add_f32_e32 v17, v6, v7
	s_waitcnt lgkmcnt(0)
	v_pk_mul_f32 v[6:7], v[30:31], v[54:55]
	v_pk_mul_f32 v[4:5], v[4:5], v[56:57]
	v_add_f32_e32 v6, v19, v6
	v_add_f32_e32 v6, v6, v7
	ds_read_b128 v[84:87], v39 offset:2032
	v_add_f32_e32 v4, v6, v4
	v_add_f32_e32 v4, v4, v5
	v_mul_f32_e64 v5, |v4|, s53
	v_exp_f32_e32 v5, v5
	s_waitcnt lgkmcnt(0)
; DI float b2f(unsigned b) { return __uint_as_float(b << 16); }
; DI float log_sigmoid(float z) { return fminf(z, 0.f) - __logf(1.f + fexp(-fabsf(z))); }
; DI void gla_gates(const P& p, int t0, int hh, char* smem, float (&bfv)[16], float (&bbv)[16], float& totf, float& totb) {
;     ...
;     bfv[j] = log_sigmoid(zf) * (1.f / 16.f);
;     bbv[j] = log_sigmoid(zb) * (1.f / 16.f);
;   }
;   float run = 0.f;
; #pragma unroll
;   for (int j = 0; j < 16; ++j) { run += bfv[j]; bfv[j] = run; }
;   tots[(0 * 4 + tg) * 64 + d] = run;
;   run = 0.f;
; #pragma unroll
;   for (int j = 15; j >= 0; --j) { run += bbv[j]; bbv[j] = run; }
;   tots[(1 * 4 + tg) * 64 + d] = run;
;   __syncthreads();
;   float offf = 0.f, offb = 0.f;
;   totf = 0.f; totb = 0.f;
; #pragma unroll
;   for (int g = 0; g < 4; ++g) {
;     float a = tots[(0 * 4 + g) * 64 + d], b = tots[(1 * 4 + g) * 64 + d];
;     totf += a; totb += b;
;     if (g < tg) offf += a;
;     if (g > tg) offb += b;
;   }
; #pragma unroll
;   for (int j = 0; j < 16; ++j) { bfv[j] += offf; bbv[j] += offb; }
; }
; DI void gla_g1_item(const P& p, int cgi, int hh, char* smem) {
;   const int tid = VT, lane = tid & 63, w = tid >> 6, d = tid & 63, tg = tid >> 6;
;   const int r16 = lane & 15, q4 = lane >> 4;
;   const int t0 = cgi * 64;
;   float bfv[16], bbv[16], totf, totb;
;   gla_gates(p, t0, hh, smem, bfv, bbv, totf, totb);
;   {
;     const long rowoff = (long)(t0 + tg * 16) * 256 + hh * 64 + d;
;     const bf16_t* gq = (const bf16_t*)(p.ws + OFF_GQ) + rowoff;
;     const bf16_t* gk = (const bf16_t*)(p.ws + OFF_GK) + rowoff;
;     bf16_t* qef = (bf16_t*)((char*)p.out + OUT_QEF) + rowoff;
;     bf16_t* kef = (bf16_t*)((char*)p.out + OUT_KEF) + rowoff;
;     bf16_t* qeb = (bf16_t*)((char*)p.out + OUT_QEB) + rowoff;
;     bf16_t* keb = (bf16_t*)((char*)p.out + OUT_KEB) + rowoff;
;     float qv[16], kv[16];
; #pragma unroll
;     for (int j = 0; j < 16; ++j) { qv[j] = b2f(gq[(long)j * 256]) * 0.125f; kv[j] = b2f(gk[(long)j * 256]); }
	v_pk_mul_f32 v[2:3], v[2:3], v[84:85]
	v_pk_mul_f32 v[0:1], v[0:1], v[86:87]
	v_add_f32_e32 v2, v17, v2
	v_add_f32_e32 v2, v2, v3
	v_add_f32_e32 v3, 1.0, v5
	v_cmp_gt_f32_e32 vcc, s54, v3
	v_add_f32_e32 v0, v2, v0
	v_add_f32_e32 v0, v0, v1
	v_cndmask_b32_e64 v5, 0, 32, vcc
	v_ldexp_f32 v3, v3, v5
	v_log_f32_e32 v3, v3
	v_min_f32_e32 v1, 0, v4
	v_mul_f32_e64 v4, |v0|, s53
	v_exp_f32_e32 v4, v4
	v_mul_f32_e32 v2, 0x3f317217, v3
	v_fma_f32 v2, v3, s55, -v2
	v_fmac_f32_e32 v2, 0x3377d1cf, v3
	v_fmac_f32_e32 v2, 0x3f317217, v3
	v_cmp_lt_f32_e64 s[16:17], |v3|, s56
	v_add_f32_e32 v4, 1.0, v4
	v_min_f32_e32 v0, 0, v0
	v_cndmask_b32_e64 v2, v3, v2, s[16:17]
	v_cndmask_b32_e32 v3, 0, v44, vcc
	v_cmp_gt_f32_e32 vcc, s54, v4
	v_sub_f32_e32 v2, v2, v3
	v_sub_f32_e32 v6, v1, v2
	v_cndmask_b32_e64 v5, 0, 32, vcc
	v_ldexp_f32 v4, v4, v5
	v_log_f32_e32 v4, v4
	v_cndmask_b32_e32 v2, 0, v44, vcc
	v_fma_f32 v17, v61, s57, 0
	v_fmamk_f32 v19, v63, 0x3d800000, v17
	v_mul_f32_e32 v1, 0x3f317217, v4
	v_fma_f32 v1, v4, s55, -v1
	v_fmac_f32_e32 v1, 0x3377d1cf, v4
	v_fmac_f32_e32 v1, 0x3f317217, v4
	v_cmp_lt_f32_e64 s[16:17], |v4|, s56
	v_fmamk_f32 v21, v65, 0x3d800000, v19
	v_fmamk_f32 v45, v67, 0x3d800000, v21
	v_cndmask_b32_e64 v1, v4, v1, s[16:17]
	v_sub_f32_e32 v1, v1, v2
	v_sub_f32_e32 v7, v0, v1
	v_or_b32_e32 v0, v26, v36
	v_ashrrev_i32_e32 v1, 31, v0
	v_lshlrev_b64 v[0:1], 8, v[0:1]
	v_or_b32_e32 v0, v0, v15
	v_or_b32_e32 v0, v0, v10
	v_lshlrev_b64 v[2:3], 1, v[0:1]
	v_fma_f32 v1, v7, s57, 0
	v_fmamk_f32 v0, v105, 0x3d800000, v1
	v_fmamk_f32 v54, v69, 0x3d800000, v45
	v_fmamk_f32 v15, v103, 0x3d800000, v0
	v_fmamk_f32 v55, v71, 0x3d800000, v54
	v_fmamk_f32 v71, v101, 0x3d800000, v15
	v_fmamk_f32 v56, v73, 0x3d800000, v55
	v_fmamk_f32 v73, v82, 0x3d800000, v71
	v_fmamk_f32 v57, v75, 0x3d800000, v56
	v_fmamk_f32 v75, v80, 0x3d800000, v73
	v_fmamk_f32 v58, v77, 0x3d800000, v57
	v_fmamk_f32 v77, v78, 0x3d800000, v75
	v_fmamk_f32 v76, v76, 0x3d800000, v77
	v_fmamk_f32 v74, v74, 0x3d800000, v76
	v_fmamk_f32 v59, v79, 0x3d800000, v58
	v_fmamk_f32 v72, v72, 0x3d800000, v74
	v_fmamk_f32 v61, v81, 0x3d800000, v59
	v_fmamk_f32 v70, v70, 0x3d800000, v72
	v_fmamk_f32 v63, v83, 0x3d800000, v61
	v_fmamk_f32 v68, v68, 0x3d800000, v70
	v_fmamk_f32 v65, v100, 0x3d800000, v63
	v_fmamk_f32 v66, v66, 0x3d800000, v68
	v_fmamk_f32 v67, v102, 0x3d800000, v65
	v_fmamk_f32 v64, v64, 0x3d800000, v66
	v_fmamk_f32 v69, v104, 0x3d800000, v67
	v_fmamk_f32 v62, v62, 0x3d800000, v64
	v_lshl_add_u64 v[4:5], s[38:39], 0, v[2:3]
	v_fmamk_f32 v60, v60, 0x3d800000, v62
	v_fmamk_f32 v7, v6, 0x3d800000, v69
	ds_write2st64_b32 v40, v7, v60 offset0:32 offset1:36
	s_waitcnt lgkmcnt(0)
	s_barrier
	global_load_ushort v78, v[4:5], off
	global_load_ushort v79, v[4:5], off offset:512
	global_load_ushort v80, v[4:5], off offset:1024
	global_load_ushort v81, v[4:5], off offset:1536
	global_load_ushort v82, v[4:5], off offset:2048
	global_load_ushort v83, v[4:5], off offset:2560
	global_load_ushort v84, v[4:5], off offset:3072
	global_load_ushort v85, v[4:5], off offset:3584
	v_add_co_u32_e32 v4, vcc, s52, v4
	v_lshl_add_u64 v[34:35], s[40:41], 0, v[2:3]
	s_nop 0
	v_addc_co_u32_e32 v5, vcc, 0, v5, vcc
	global_load_ushort v86, v[4:5], off
	global_load_ushort v87, v[4:5], off offset:512
	global_load_ushort v88, v[4:5], off offset:1024
	global_load_ushort v89, v[4:5], off offset:1536
	global_load_ushort v90, v[4:5], off offset:2048
	global_load_ushort v91, v[4:5], off offset:2560
	global_load_ushort v92, v[4:5], off offset:3072
	ds_read2st64_b32 v[28:29], v41 offset0:32 offset1:33
	global_load_ushort v4, v[4:5], off offset:3584
	v_lshl_add_u64 v[50:51], s[36:37], 0, v[2:3]
	v_lshl_add_u64 v[30:31], s[42:43], 0, v[2:3]
	v_lshl_add_u64 v[52:53], s[44:45], 0, v[2:3]
	v_lshl_add_u64 v[32:33], s[46:47], 0, v[2:3]
	ds_read2st64_b32 v[48:49], v41 offset0:36 offset1:37
	ds_read2st64_b32 v[2:3], v41 offset0:38 offset1:39
	ds_read2st64_b32 v[46:47], v41 offset0:34 offset1:35
	s_waitcnt lgkmcnt(3)
	v_add_f32_e32 v5, 0, v28
	v_cndmask_b32_e64 v6, v5, 0, s[4:5]
	v_add_f32_e32 v28, v6, v29
	v_add_f32_e32 v5, v5, v29
	v_cndmask_b32_e64 v28, v6, v28, s[6:7]
	s_waitcnt lgkmcnt(2)
	v_add_f32_e32 v6, 0, v49
	v_cndmask_b32_e64 v93, 0, v6, s[4:5]
	s_waitcnt lgkmcnt(0)
	v_add_f32_e32 v6, v5, v46
	v_add_f32_e32 v5, v28, v46
	v_cndmask_b32_e64 v29, v28, v5, s[8:9]
	v_add_f32_e32 v5, v93, v2
	v_cndmask_b32_e64 v5, 0, v5, s[10:11]
	v_add_f32_e32 v28, v5, v3
	v_cndmask_b32_e64 v5, v28, v5, s[8:9]
	v_add_f32_e32 v94, v19, v29
	v_add_f32_e32 v19, v15, v5
	v_add_f32_e32 v15, v0, v5
	v_add_f32_e32 v46, v65, v29
	v_add_f32_e32 v96, v45, v29
	v_add_f32_e32 v45, v67, v29
	v_add_f32_e32 v93, v17, v29
	v_add_f32_e32 v17, v69, v29
	v_add_f32_e32 v95, v21, v29
	v_add_f32_e32 v21, v71, v5
	v_add_f32_e32 v60, v5, v60
	v_mov_b32_e32 v28, v47
	v_add_f32_e32 v54, v54, v29
	v_add_f32_e32 v55, v55, v29
	v_add_f32_e32 v56, v56, v29
	v_add_f32_e32 v57, v57, v29
	v_add_f32_e32 v58, v58, v29
	v_add_f32_e32 v59, v59, v29
	v_add_f32_e32 v61, v61, v29
	v_add_f32_e32 v63, v63, v29
	v_pk_add_f32 v[28:29], v[6:7], v[28:29]
	v_add_co_u32_e32 v6, vcc, s52, v34
	v_add_f32_e32 v62, v5, v62
	s_nop 0
	v_addc_co_u32_e32 v7, vcc, 0, v35, vcc
	v_add_f32_e32 v64, v5, v64
	v_add_f32_e32 v66, v5, v66
	v_add_f32_e32 v68, v5, v68
	v_add_f32_e32 v70, v5, v70
	v_add_f32_e32 v72, v5, v72
	v_add_f32_e32 v74, v5, v74
	v_add_f32_e32 v76, v5, v76
	v_add_f32_e32 v77, v5, v77
	v_add_f32_e32 v75, v5, v75
	v_add_f32_e32 v73, v73, v5
	s_waitcnt vmcnt(15)
	v_lshlrev_b32_e32 v0, 16, v78
	v_mul_f32_e32 v65, 0x3e000000, v0
	s_waitcnt vmcnt(14)
	v_lshlrev_b32_e32 v0, 16, v79
	v_mul_f32_e32 v67, 0x3e000000, v0
	s_waitcnt vmcnt(13)
; DI float b2f(unsigned b) { return __uint_as_float(b << 16); }
; DI float fexp(float x) { return __builtin_amdgcn_exp2f(x * LOG2E); }
; DI void gla_g1_item(const P& p, int cgi, int hh, char* smem) {
;     ...
;     for (int j = 0; j < 16; ++j) { qv[j] = b2f(gq[(long)j * 256]) * 0.125f; kv[j] = b2f(gk[(long)j * 256]); }
;     unsigned pf[8], pb[8];
; #pragma unroll
;     for (int j = 0; j < 16; ++j) {
;       float ef = fexp(bfv[j]), eb = fexp(bbv[j]);
;       qef[(long)j * 256] = f2b(qv[j] * ef);
;       qeb[(long)j * 256] = f2b(qv[j] * eb);
;       kef[(long)j * 256] = f2b(kv[j] * fexp(-bfv[j]));
;       keb[(long)j * 256] = f2b(kv[j] * fexp(-bbv[j]));
;     }
	v_lshlrev_b32_e32 v0, 16, v80
	v_mul_f32_e32 v69, 0x3e000000, v0
	s_waitcnt vmcnt(12)
	v_lshlrev_b32_e32 v0, 16, v81
	v_mul_f32_e32 v71, 0x3e000000, v0
	s_waitcnt vmcnt(11)
	v_lshlrev_b32_e32 v0, 16, v82
	v_mul_f32_e32 v78, 0x3e000000, v0
	s_waitcnt vmcnt(10)
	v_lshlrev_b32_e32 v0, 16, v83
	v_mul_f32_e32 v79, 0x3e000000, v0
	s_waitcnt vmcnt(9)
	v_lshlrev_b32_e32 v0, 16, v84
	v_mul_f32_e32 v80, 0x3e000000, v0
	s_waitcnt vmcnt(8)
	v_lshlrev_b32_e32 v0, 16, v85
	v_mul_f32_e32 v81, 0x3e000000, v0
	s_waitcnt vmcnt(7)
	v_lshlrev_b32_e32 v0, 16, v86
	v_mul_f32_e32 v82, 0x3e000000, v0
	s_waitcnt vmcnt(6)
	v_lshlrev_b32_e32 v0, 16, v87
	v_mul_f32_e32 v83, 0x3e000000, v0
	s_waitcnt vmcnt(5)
	v_lshlrev_b32_e32 v0, 16, v88
	v_mul_f32_e32 v84, 0x3e000000, v0
	s_waitcnt vmcnt(4)
	v_lshlrev_b32_e32 v0, 16, v89
	v_mul_f32_e32 v85, 0x3e000000, v0
	s_waitcnt vmcnt(3)
	v_lshlrev_b32_e32 v0, 16, v90
	v_mul_f32_e32 v86, 0x3e000000, v0
	s_waitcnt vmcnt(2)
	v_lshlrev_b32_e32 v0, 16, v91
	v_mul_f32_e32 v87, 0x3e000000, v0
	s_waitcnt vmcnt(1)
	v_lshlrev_b32_e32 v0, 16, v92
	v_mul_f32_e32 v88, 0x3e000000, v0
	s_waitcnt vmcnt(0)
	v_lshlrev_b32_e32 v0, 16, v4
	v_mul_f32_e32 v89, 0x3e000000, v0
	v_add_f32_e32 v0, 0, v48
	v_add_f32_e32 v0, v0, v49
	v_mul_f32_e32 v4, 0x3fb8aa3b, v93
	v_add_f32_e32 v0, v0, v2
	v_mul_f32_e32 v2, 0x3fb8aa3b, v60
	v_exp_f32_e32 v4, v4
	v_exp_f32_e32 v2, v2
	global_load_ushort v49, v[34:35], off
	global_load_ushort v90, v[34:35], off offset:512
	global_load_ushort v91, v[34:35], off offset:1024
	global_load_ushort v92, v[34:35], off offset:1536
	global_load_ushort v97, v[34:35], off offset:2048
	global_load_ushort v98, v[34:35], off offset:2560
	global_load_ushort v99, v[34:35], off offset:3072
	global_load_ushort v100, v[34:35], off offset:3584
	global_load_ushort v101, v[6:7], off
	global_load_ushort v102, v[6:7], off offset:512
	global_load_ushort v103, v[6:7], off offset:1024
	global_load_ushort v104, v[6:7], off offset:1536
	global_load_ushort v105, v[6:7], off offset:2048
	global_load_ushort v106, v[6:7], off offset:2560
	global_load_ushort v47, v[6:7], off offset:3072
	global_load_ushort v48, v[6:7], off offset:3584
	v_mul_f32_e32 v4, v4, v65
	v_mul_f32_e32 v2, v65, v2
	v_cvt_pk_bf16_f32 v4, v4, s0
	v_cvt_pk_bf16_f32 v2, v2, s0
	global_store_short v[50:51], v4, off
	global_store_short v[52:53], v2, off
	v_mul_f32_e32 v2, 0xbfb8aa3b, v93
	v_exp_f32_e32 v65, v2
	v_mul_f32_e32 v2, 0xbfb8aa3b, v60
	v_mul_f32_e32 v4, 0x3fb8aa3b, v94
	v_exp_f32_e32 v107, v2
	v_mul_f32_e32 v2, 0x3fb8aa3b, v62
	v_exp_f32_e32 v4, v4
	v_exp_f32_e32 v2, v2
	v_add_co_u32_e32 v6, vcc, s52, v50
	v_mul_f32_e32 v4, v4, v67
	v_mul_f32_e32 v2, v67, v2
	v_cvt_pk_bf16_f32 v4, v4, s0
	v_cvt_pk_bf16_f32 v2, v2, s0
	global_store_short v[50:51], v4, off offset:512
	global_store_short v[52:53], v2, off offset:512
	v_mul_f32_e32 v2, 0xbfb8aa3b, v94
	v_exp_f32_e32 v67, v2
	v_mul_f32_e32 v2, 0xbfb8aa3b, v62
	v_mul_f32_e32 v4, 0x3fb8aa3b, v95
	v_exp_f32_e32 v108, v2
	v_mul_f32_e32 v2, 0x3fb8aa3b, v64
	v_exp_f32_e32 v4, v4
	v_exp_f32_e32 v2, v2
	v_addc_co_u32_e32 v7, vcc, 0, v51, vcc
	v_mul_f32_e32 v4, v4, v69
	v_mul_f32_e32 v2, v69, v2
	v_cvt_pk_bf16_f32 v4, v4, s0
	v_cvt_pk_bf16_f32 v2, v2, s0
	global_store_short v[50:51], v4, off offset:1024
	global_store_short v[52:53], v2, off offset:1024
	v_mul_f32_e32 v2, 0xbfb8aa3b, v95
	v_exp_f32_e32 v69, v2
	v_mul_f32_e32 v2, 0xbfb8aa3b, v64
	v_mul_f32_e32 v4, 0x3fb8aa3b, v96
	v_exp_f32_e32 v109, v2
	v_mul_f32_e32 v2, 0x3fb8aa3b, v66
	v_exp_f32_e32 v4, v4
	v_exp_f32_e32 v2, v2
	v_mul_f32_e32 v4, v4, v71
	v_mul_f32_e32 v2, v71, v2
	v_cvt_pk_bf16_f32 v4, v4, s0
	v_cvt_pk_bf16_f32 v2, v2, s0
	global_store_short v[50:51], v4, off offset:1536
	global_store_short v[52:53], v2, off offset:1536
	v_mul_f32_e32 v2, 0xbfb8aa3b, v96
	v_exp_f32_e32 v71, v2
	v_mul_f32_e32 v2, 0xbfb8aa3b, v66
	v_mul_f32_e32 v4, 0x3fb8aa3b, v54
	v_exp_f32_e32 v110, v2
	v_mul_f32_e32 v2, 0x3fb8aa3b, v68
	v_exp_f32_e32 v4, v4
	v_exp_f32_e32 v2, v2
	v_mul_f32_e32 v4, v4, v78
	v_mul_f32_e32 v2, v2, v78
	v_cvt_pk_bf16_f32 v4, v4, s0
	v_cvt_pk_bf16_f32 v2, v2, s0
	global_store_short v[50:51], v4, off offset:2048
	global_store_short v[52:53], v2, off offset:2048
	v_mul_f32_e32 v2, 0xbfb8aa3b, v54
	v_exp_f32_e32 v78, v2
	v_mul_f32_e32 v2, 0xbfb8aa3b, v68
	v_mul_f32_e32 v4, 0x3fb8aa3b, v55
	v_exp_f32_e32 v111, v2
	v_mul_f32_e32 v2, 0x3fb8aa3b, v70
	v_exp_f32_e32 v4, v4
	v_exp_f32_e32 v2, v2
	v_mul_f32_e32 v4, v4, v79
	v_mul_f32_e32 v2, v2, v79
	v_cvt_pk_bf16_f32 v4, v4, s0
	v_cvt_pk_bf16_f32 v2, v2, s0
	global_store_short v[50:51], v4, off offset:2560
	global_store_short v[52:53], v2, off offset:2560
	v_mul_f32_e32 v2, 0xbfb8aa3b, v55
	v_exp_f32_e32 v79, v2
	v_mul_f32_e32 v2, 0xbfb8aa3b, v70
	v_mul_f32_e32 v4, 0x3fb8aa3b, v56
	v_exp_f32_e32 v112, v2
	v_mul_f32_e32 v2, 0x3fb8aa3b, v72
	v_exp_f32_e32 v4, v4
	v_exp_f32_e32 v2, v2
	v_mul_f32_e32 v4, v4, v80
	v_mul_f32_e32 v2, v2, v80
	v_cvt_pk_bf16_f32 v4, v4, s0
	v_cvt_pk_bf16_f32 v2, v2, s0
	global_store_short v[50:51], v4, off offset:3072
	global_store_short v[52:53], v2, off offset:3072
	v_mul_f32_e32 v2, 0xbfb8aa3b, v56
	v_exp_f32_e32 v80, v2
	v_mul_f32_e32 v2, 0xbfb8aa3b, v72
	v_mul_f32_e32 v4, 0x3fb8aa3b, v57
	v_exp_f32_e32 v113, v2
	v_mul_f32_e32 v2, 0x3fb8aa3b, v74
	v_exp_f32_e32 v4, v4
	v_exp_f32_e32 v2, v2
	v_mul_f32_e32 v4, v4, v81
	v_mul_f32_e32 v2, v2, v81
	v_cvt_pk_bf16_f32 v4, v4, s0
	v_cvt_pk_bf16_f32 v2, v2, s0
	global_store_short v[50:51], v4, off offset:3584
	global_store_short v[52:53], v2, off offset:3584
	v_mul_f32_e32 v2, 0xbfb8aa3b, v57
	v_exp_f32_e32 v81, v2
	v_mul_f32_e32 v2, 0xbfb8aa3b, v74
	v_mul_f32_e32 v4, 0x3fb8aa3b, v58
	v_exp_f32_e32 v114, v2
	v_mul_f32_e32 v2, 0x3fb8aa3b, v76
	v_exp_f32_e32 v4, v4
	v_exp_f32_e32 v2, v2
	v_add_co_u32_e32 v50, vcc, s52, v52
	v_mul_f32_e32 v4, v4, v82
	v_mul_f32_e32 v2, v2, v82
	v_cvt_pk_bf16_f32 v4, v4, s0
	v_cvt_pk_bf16_f32 v2, v2, s0
	v_addc_co_u32_e32 v51, vcc, 0, v53, vcc
	global_store_short v[6:7], v4, off
	global_store_short v[50:51], v2, off
	v_mul_f32_e32 v2, 0xbfb8aa3b, v58
	v_exp_f32_e32 v82, v2
	v_mul_f32_e32 v2, 0xbfb8aa3b, v76
	v_mul_f32_e32 v4, 0x3fb8aa3b, v59
	v_exp_f32_e32 v115, v2
	v_mul_f32_e32 v2, 0x3fb8aa3b, v77
	v_exp_f32_e32 v4, v4
	v_exp_f32_e32 v2, v2
	s_waitcnt vmcnt(27)
; DI float fexp(float x) { return __builtin_amdgcn_exp2f(x * LOG2E); }
; DI void gla_g1_item(const P& p, int cgi, int hh, char* smem) {
;     ...
;     for (int j = 0; j < 16; ++j) {
;       float ef = fexp(bfv[j]), eb = fexp(bbv[j]);
;       qef[(long)j * 256] = f2b(qv[j] * ef);
;       qeb[(long)j * 256] = f2b(qv[j] * eb);
;       kef[(long)j * 256] = f2b(kv[j] * fexp(-bfv[j]));
;       keb[(long)j * 256] = f2b(kv[j] * fexp(-bbv[j]));
;     }
; #pragma unroll
;     for (int j = 0; j < 8; ++j) {
;       pf[j] = pk2(kv[2 * j] * fexp(totf - bfv[2 * j]), kv[2 * j + 1] * fexp(totf - bfv[2 * j + 1]));
;       pb[j] = pk2(kv[2 * j] * fexp(totb - bbv[2 * j]), kv[2 * j + 1] * fexp(totb - bbv[2 * j + 1]));
;     }
	v_lshlrev_b32_e32 v52, 16, v99
	s_waitcnt vmcnt(26)
	v_lshlrev_b32_e32 v53, 16, v100
	v_mul_f32_e32 v4, v4, v83
	v_mul_f32_e32 v2, v2, v83
	v_cvt_pk_bf16_f32 v4, v4, s0
	v_cvt_pk_bf16_f32 v2, v2, s0
	global_store_short v[6:7], v4, off offset:512
	global_store_short v[50:51], v2, off offset:512
	v_mul_f32_e32 v2, 0xbfb8aa3b, v59
	v_exp_f32_e32 v83, v2
	v_mul_f32_e32 v2, 0xbfb8aa3b, v77
	v_mul_f32_e32 v4, 0x3fb8aa3b, v61
	v_exp_f32_e32 v116, v2
	v_mul_f32_e32 v2, 0x3fb8aa3b, v75
	v_exp_f32_e32 v4, v4
	v_exp_f32_e32 v2, v2
	v_mul_f32_e32 v4, v4, v84
	v_mul_f32_e32 v2, v2, v84
	v_cvt_pk_bf16_f32 v4, v4, s0
	v_cvt_pk_bf16_f32 v2, v2, s0
	global_store_short v[6:7], v4, off offset:1024
	global_store_short v[50:51], v2, off offset:1024
	v_mul_f32_e32 v2, 0xbfb8aa3b, v61
	v_exp_f32_e32 v84, v2
	v_mul_f32_e32 v2, 0xbfb8aa3b, v75
	v_mul_f32_e32 v4, 0x3fb8aa3b, v63
	v_exp_f32_e32 v117, v2
	v_mul_f32_e32 v2, 0x3fb8aa3b, v73
	v_exp_f32_e32 v4, v4
	v_exp_f32_e32 v2, v2
	v_mul_f32_e32 v4, v4, v85
	v_mul_f32_e32 v2, v2, v85
	v_cvt_pk_bf16_f32 v4, v4, s0
	v_cvt_pk_bf16_f32 v2, v2, s0
	global_store_short v[6:7], v4, off offset:1536
	global_store_short v[50:51], v2, off offset:1536
	v_mul_f32_e32 v2, 0xbfb8aa3b, v63
	v_exp_f32_e32 v85, v2
	v_mul_f32_e32 v2, 0xbfb8aa3b, v73
	v_mul_f32_e32 v4, 0x3fb8aa3b, v46
	v_exp_f32_e32 v118, v2
	v_mul_f32_e32 v2, 0x3fb8aa3b, v21
	v_exp_f32_e32 v4, v4
	v_exp_f32_e32 v2, v2
	v_mul_f32_e32 v4, v4, v86
	v_mul_f32_e32 v2, v2, v86
	v_cvt_pk_bf16_f32 v4, v4, s0
	v_cvt_pk_bf16_f32 v2, v2, s0
	global_store_short v[6:7], v4, off offset:2048
	global_store_short v[50:51], v2, off offset:2048
	v_mul_f32_e32 v2, 0xbfb8aa3b, v46
	v_exp_f32_e32 v86, v2
	v_mul_f32_e32 v2, 0xbfb8aa3b, v21
	v_mul_f32_e32 v4, 0x3fb8aa3b, v45
	v_exp_f32_e32 v119, v2
	v_mul_f32_e32 v2, 0x3fb8aa3b, v19
	v_exp_f32_e32 v4, v4
	v_exp_f32_e32 v2, v2
	v_mul_f32_e32 v4, v4, v87
	v_mul_f32_e32 v2, v2, v87
	v_cvt_pk_bf16_f32 v4, v4, s0
	v_cvt_pk_bf16_f32 v2, v2, s0
	global_store_short v[6:7], v4, off offset:2560
	global_store_short v[50:51], v2, off offset:2560
	v_mul_f32_e32 v2, 0xbfb8aa3b, v45
	v_exp_f32_e32 v87, v2
	v_mul_f32_e32 v2, 0xbfb8aa3b, v19
	v_mul_f32_e32 v4, 0x3fb8aa3b, v17
	v_exp_f32_e32 v120, v2
	v_mul_f32_e32 v2, 0x3fb8aa3b, v15
	v_exp_f32_e32 v4, v4
	v_exp_f32_e32 v2, v2
	v_mul_f32_e32 v4, v4, v88
	v_mul_f32_e32 v2, v2, v88
	v_cvt_pk_bf16_f32 v4, v4, s0
	v_cvt_pk_bf16_f32 v2, v2, s0
	global_store_short v[6:7], v4, off offset:3072
	global_store_short v[50:51], v2, off offset:3072
	v_mul_f32_e32 v2, 0xbfb8aa3b, v17
	v_mov_b32_e32 v4, v3
	v_exp_f32_e32 v88, v2
	v_mul_f32_e32 v2, 0xbfb8aa3b, v15
	v_pk_add_f32 v[34:35], v[0:1], v[4:5]
	v_exp_f32_e32 v121, v2
	v_mul_f32_e32 v2, 0x3fb8aa3b, v29
	v_mul_f32_e32 v0, 0x3fb8aa3b, v35
	v_exp_f32_e32 v2, v2
	v_exp_f32_e32 v0, v0
	v_lshlrev_b32_e32 v3, 16, v90
	v_sub_f32_e32 v19, v34, v19
	v_mul_f32_e32 v1, v2, v89
	v_mul_f32_e32 v0, v0, v89
	v_cvt_pk_bf16_f32 v1, v1, s0
	v_cvt_pk_bf16_f32 v0, v0, s0
	global_store_short v[6:7], v1, off offset:3584
	global_store_short v[50:51], v0, off offset:3584
	v_mul_f32_e32 v0, 0xbfb8aa3b, v29
	v_exp_f32_e32 v89, v0
	v_mul_f32_e32 v0, 0xbfb8aa3b, v35
	v_exp_f32_e32 v122, v0
	v_sub_f32_e32 v0, v28, v93
	v_mul_f32_e32 v0, 0x3fb8aa3b, v0
	v_lshlrev_b32_e32 v2, 16, v49
	v_exp_f32_e32 v4, v0
	v_sub_f32_e32 v0, v28, v94
	v_mul_f32_e32 v6, v65, v2
	v_mul_f32_e32 v0, 0x3fb8aa3b, v0
	v_cvt_pk_bf16_f32 v6, v6, s0
	v_exp_f32_e32 v5, v0
	v_sub_f32_e32 v0, v34, v60
	v_sub_f32_e32 v1, v34, v62
	global_store_short v[30:31], v6, off
	v_mul_f32_e32 v6, v107, v2
	v_mul_f32_e32 v0, 0x3fb8aa3b, v0
	v_mul_f32_e32 v1, 0x3fb8aa3b, v1
	v_cvt_pk_bf16_f32 v6, v6, s0
	v_exp_f32_e32 v0, v0
	v_exp_f32_e32 v1, v1
	global_store_short v[32:33], v6, off
	v_mul_f32_e32 v6, v67, v3
	v_cvt_pk_bf16_f32 v6, v6, s0
	global_store_short v[30:31], v6, off offset:512
	v_mul_f32_e32 v6, v108, v3
	v_cvt_pk_bf16_f32 v6, v6, s0
	global_store_short v[32:33], v6, off offset:512
	v_mul_f32_e32 v4, v4, v2
	v_pk_mul_f32 v[0:1], v[0:1], v[2:3]
	v_sub_f32_e32 v2, v28, v96
	v_lshlrev_b32_e32 v6, 16, v91
	v_mul_f32_e32 v5, v5, v3
	v_mul_f32_e32 v2, 0x3fb8aa3b, v2
	v_mul_f32_e32 v49, v69, v6
	v_cvt_pk_bf16_f32 v4, v4, v5
	v_cvt_pk_bf16_f32 v0, v0, v1
	v_sub_f32_e32 v1, v28, v95
	v_exp_f32_e32 v5, v2
	v_sub_f32_e32 v2, v34, v64
	v_sub_f32_e32 v3, v34, v66
	v_cvt_pk_bf16_f32 v49, v49, s0
	v_mul_f32_e32 v1, 0x3fb8aa3b, v1
	v_mul_f32_e32 v2, 0x3fb8aa3b, v2
	v_mul_f32_e32 v3, 0x3fb8aa3b, v3
	global_store_short v[30:31], v49, off offset:1024
	v_mul_f32_e32 v49, v109, v6
	v_exp_f32_e32 v1, v1
	v_exp_f32_e32 v2, v2
	v_exp_f32_e32 v3, v3
	v_lshlrev_b32_e32 v7, 16, v92
	v_cvt_pk_bf16_f32 v49, v49, s0
	global_store_short v[32:33], v49, off offset:1024
	v_mul_f32_e32 v49, v71, v7
	v_cvt_pk_bf16_f32 v49, v49, s0
	global_store_short v[30:31], v49, off offset:1536
	v_mul_f32_e32 v49, v110, v7
	v_cvt_pk_bf16_f32 v49, v49, s0
	v_mul_f32_e32 v1, v1, v6
	v_mul_f32_e32 v5, v5, v7
	v_pk_mul_f32 v[2:3], v[2:3], v[6:7]
	v_lshlrev_b32_e32 v50, 16, v97
	global_store_short v[32:33], v49, off offset:1536
	v_cvt_pk_bf16_f32 v5, v1, v5
	v_cvt_pk_bf16_f32 v1, v2, v3
	v_sub_f32_e32 v2, v28, v54
	v_mul_f32_e32 v49, v78, v50
	v_mul_f32_e32 v2, 0x3fb8aa3b, v2
	v_cvt_pk_bf16_f32 v49, v49, s0
	v_exp_f32_e32 v6, v2
	v_sub_f32_e32 v2, v28, v55
	global_store_short v[30:31], v49, off offset:2048
	v_mul_f32_e32 v49, v111, v50
	v_mul_f32_e32 v2, 0x3fb8aa3b, v2
	v_lshlrev_b32_e32 v51, 16, v98
	v_cvt_pk_bf16_f32 v49, v49, s0
	v_exp_f32_e32 v7, v2
	v_sub_f32_e32 v2, v34, v68
	v_sub_f32_e32 v3, v34, v70
	global_store_short v[32:33], v49, off offset:2048
	v_mul_f32_e32 v49, v79, v51
	v_mul_f32_e32 v2, 0x3fb8aa3b, v2
	v_mul_f32_e32 v3, 0x3fb8aa3b, v3
	v_cvt_pk_bf16_f32 v49, v49, s0
	v_exp_f32_e32 v2, v2
	v_exp_f32_e32 v3, v3
	global_store_short v[30:31], v49, off offset:2560
	v_mul_f32_e32 v49, v112, v51
	v_cvt_pk_bf16_f32 v49, v49, s0
	global_store_short v[32:33], v49, off offset:2560
	v_sub_f32_e32 v49, v34, v72
	v_mul_f32_e32 v49, 0x3fb8aa3b, v49
	v_mul_f32_e32 v6, v6, v50
	v_mul_f32_e32 v7, v7, v51
	v_pk_mul_f32 v[2:3], v[2:3], v[50:51]
	v_exp_f32_e32 v50, v49
	v_sub_f32_e32 v49, v34, v74
	v_cvt_pk_bf16_f32 v6, v6, v7
	v_cvt_pk_bf16_f32 v2, v2, v3
	v_sub_f32_e32 v3, v28, v56
	v_sub_f32_e32 v7, v28, v57
	v_mul_f32_e32 v49, 0x3fb8aa3b, v49
	v_mul_f32_e32 v3, 0x3fb8aa3b, v3
	v_mul_f32_e32 v7, 0x3fb8aa3b, v7
	v_exp_f32_e32 v51, v49
	v_mul_f32_e32 v49, v80, v52
	v_exp_f32_e32 v3, v3
	v_exp_f32_e32 v7, v7
	v_cvt_pk_bf16_f32 v49, v49, s0
	global_store_short v[30:31], v49, off offset:3072
	v_mul_f32_e32 v49, v113, v52
	v_cvt_pk_bf16_f32 v49, v49, s0
	global_store_short v[32:33], v49, off offset:3072
	v_mul_f32_e32 v49, v81, v53
	v_cvt_pk_bf16_f32 v49, v49, s0
	v_mul_f32_e32 v3, v3, v52
	v_mul_f32_e32 v7, v7, v53
	v_pk_mul_f32 v[50:51], v[50:51], v[52:53]
	global_store_short v[30:31], v49, off offset:3584
	v_mul_f32_e32 v49, v114, v53
	v_cvt_pk_bf16_f32 v7, v3, v7
	v_cvt_pk_bf16_f32 v3, v50, v51
	v_sub_f32_e32 v50, v28, v59
	s_waitcnt vmcnt(54)
; DI float fexp(float x) { return __builtin_amdgcn_exp2f(x * LOG2E); }
; DI void gla_g1_item(const P& p, int cgi, int hh, char* smem) {
;     ...
;       kef[(long)j * 256] = f2b(kv[j] * fexp(-bfv[j]));
;       keb[(long)j * 256] = f2b(kv[j] * fexp(-bbv[j]));
;     }
; #pragma unroll
;     for (int j = 0; j < 8; ++j) {
;       pf[j] = pk2(kv[2 * j] * fexp(totf - bfv[2 * j]), kv[2 * j + 1] * fexp(totf - bfv[2 * j + 1]));
;       pb[j] = pk2(kv[2 * j] * fexp(totb - bbv[2 * j]), kv[2 * j + 1] * fexp(totb - bbv[2 * j + 1]));
;     }
;     char* d1 = smem + GL_B1 + d * GROW + tg * 32;
;     char* d2 = smem + GL_B2 + d * GROW + tg * 32;
;     *(u4*)(d1) = u4{pf[0], pf[1], pf[2], pf[3]};
;     *(u4*)(d1 + 16) = u4{pf[4], pf[5], pf[6], pf[7]};
;     *(u4*)(d2) = u4{pb[0], pb[1], pb[2], pb[3]};
;     *(u4*)(d2 + 16) = u4{pb[4], pb[5], pb[6], pb[7]};
;   }
;   if (tg == 0) {
;     float* dec = (float*)(p.ws + OFF_DEC) + (long)((cgi * 4 + hh) * 2) * 64;
;     dec[d] = fexp(totf);
;     dec[64 + d] = fexp(totb);
;   }
	v_lshlrev_b32_e32 v52, 16, v101
	v_cvt_pk_bf16_f32 v49, v49, s0
	v_mul_f32_e32 v50, 0x3fb8aa3b, v50
	v_mul_f32_e32 v54, v82, v52
	global_store_short v[32:33], v49, off offset:3584
	v_sub_f32_e32 v49, v28, v58
	v_exp_f32_e32 v58, v50
	v_sub_f32_e32 v50, v34, v76
	v_sub_f32_e32 v51, v34, v77
	v_cvt_pk_bf16_f32 v56, v54, s0
	v_add_co_u32_e32 v54, vcc, s52, v30
	v_mul_f32_e32 v50, 0x3fb8aa3b, v50
	v_mul_f32_e32 v51, 0x3fb8aa3b, v51
	v_addc_co_u32_e32 v55, vcc, 0, v31, vcc
	v_exp_f32_e32 v50, v50
	v_exp_f32_e32 v51, v51
	global_store_short v[54:55], v56, off
	v_mul_f32_e32 v30, v115, v52
	v_add_co_u32_e32 v56, vcc, s52, v32
	v_mul_f32_e32 v49, 0x3fb8aa3b, v49
	s_waitcnt vmcnt(55)
	v_lshlrev_b32_e32 v53, 16, v102
	v_cvt_pk_bf16_f32 v30, v30, s0
	v_addc_co_u32_e32 v57, vcc, 0, v33, vcc
	v_exp_f32_e32 v49, v49
	global_store_short v[56:57], v30, off
	v_mul_f32_e32 v30, v83, v53
	v_cvt_pk_bf16_f32 v30, v30, s0
	global_store_short v[54:55], v30, off offset:512
	v_mul_f32_e32 v30, v116, v53
	v_pk_mul_f32 v[32:33], v[50:51], v[52:53]
	v_cvt_pk_bf16_f32 v30, v30, s0
	v_cvt_pk_bf16_f32 v50, v32, v33
	v_sub_f32_e32 v32, v28, v63
	global_store_short v[56:57], v30, off offset:512
	v_mul_f32_e32 v30, v49, v52
	v_mul_f32_e32 v32, 0x3fb8aa3b, v32
	s_waitcnt vmcnt(57)
	v_lshlrev_b32_e32 v52, 16, v103
	v_exp_f32_e32 v49, v32
	v_sub_f32_e32 v32, v34, v75
	v_sub_f32_e32 v33, v34, v73
	v_mul_f32_e32 v51, v84, v52
	v_mul_f32_e32 v32, 0x3fb8aa3b, v32
	v_mul_f32_e32 v33, 0x3fb8aa3b, v33
	v_cvt_pk_bf16_f32 v51, v51, s0
	v_exp_f32_e32 v32, v32
	v_exp_f32_e32 v33, v33
	global_store_short v[54:55], v51, off offset:1024
	v_mul_f32_e32 v51, v117, v52
	v_mul_f32_e32 v31, v58, v53
	s_waitcnt vmcnt(57)
	v_lshlrev_b32_e32 v53, 16, v104
	v_cvt_pk_bf16_f32 v51, v51, s0
	v_cvt_pk_bf16_f32 v30, v30, v31
	v_sub_f32_e32 v31, v28, v61
	global_store_short v[56:57], v51, off offset:1024
	v_mul_f32_e32 v51, v85, v53
	v_mul_f32_e32 v31, 0x3fb8aa3b, v31
	v_cvt_pk_bf16_f32 v51, v51, s0
	v_mul_f32_e32 v19, 0x3fb8aa3b, v19
	s_waitcnt vmcnt(57)
	v_lshlrev_b32_e32 v58, 16, v105
	v_exp_f32_e32 v31, v31
	global_store_short v[54:55], v51, off offset:1536
	v_mul_f32_e32 v51, v118, v53
	v_mul_f32_e32 v49, v49, v53
	v_pk_mul_f32 v[32:33], v[32:33], v[52:53]
	v_exp_f32_e32 v53, v19
	v_mul_f32_e32 v19, v86, v58
	v_cvt_pk_bf16_f32 v51, v51, s0
	v_cvt_pk_bf16_f32 v19, v19, s0
	global_store_short v[56:57], v51, off offset:1536
	v_cvt_pk_bf16_f32 v51, v32, v33
	v_sub_f32_e32 v32, v28, v46
	v_sub_f32_e32 v21, v34, v21
	global_store_short v[54:55], v19, off offset:2048
	v_mul_f32_e32 v19, v119, v58
	v_mul_f32_e32 v32, 0x3fb8aa3b, v32
	v_mul_f32_e32 v21, 0x3fb8aa3b, v21
	s_waitcnt vmcnt(59)
	v_lshlrev_b32_e32 v59, 16, v106
	v_cvt_pk_bf16_f32 v19, v19, s0
	v_mul_f32_e32 v31, v31, v52
	v_exp_f32_e32 v32, v32
	v_sub_f32_e32 v33, v28, v45
	v_exp_f32_e32 v52, v21
	global_store_short v[56:57], v19, off offset:2048
	v_mul_f32_e32 v19, v87, v59
	v_mul_f32_e32 v33, 0x3fb8aa3b, v33
	v_cvt_pk_bf16_f32 v19, v19, s0
	v_exp_f32_e32 v33, v33
	global_store_short v[54:55], v19, off offset:2560
	v_mul_f32_e32 v19, v120, v59
	v_sub_f32_e32 v15, v34, v15
	v_cvt_pk_bf16_f32 v19, v19, s0
	v_mul_f32_e32 v15, 0x3fb8aa3b, v15
	global_store_short v[56:57], v19, off offset:2560
	v_mul_f32_e32 v19, v32, v58
	v_pk_mul_f32 v[52:53], v[52:53], v[58:59]
	v_exp_f32_e32 v58, v15
	v_sub_f32_e32 v15, v34, v35
	v_cvt_pk_bf16_f32 v31, v31, v49
	v_mul_f32_e32 v15, 0x3fb8aa3b, v15
	s_waitcnt vmcnt(60)
	v_lshlrev_b32_e32 v49, 16, v48
	v_lshlrev_b32_e32 v48, 16, v47
	v_mul_f32_e32 v21, v33, v59
	v_exp_f32_e32 v59, v15
	v_mul_f32_e32 v15, v88, v48
	v_cvt_pk_bf16_f32 v15, v15, s0
	v_cvt_pk_bf16_f32 v32, v19, v21
	v_sub_f32_e32 v17, v28, v17
	v_sub_f32_e32 v19, v28, v29
	global_store_short v[54:55], v15, off offset:3072
	v_mul_f32_e32 v15, v121, v48
	v_mul_f32_e32 v17, 0x3fb8aa3b, v17
	v_mul_f32_e32 v19, 0x3fb8aa3b, v19
	v_cvt_pk_bf16_f32 v15, v15, s0
	v_exp_f32_e32 v17, v17
	v_exp_f32_e32 v19, v19
	global_store_short v[56:57], v15, off offset:3072
	v_mul_f32_e32 v15, v89, v49
	v_cvt_pk_bf16_f32 v15, v15, s0
	global_store_short v[54:55], v15, off offset:3584
	v_mul_f32_e32 v15, v122, v49
	v_cvt_pk_bf16_f32 v15, v15, s0
	global_store_short v[56:57], v15, off offset:3584
	v_mul_f32_e32 v15, v17, v48
	v_mul_f32_e32 v17, v19, v49
	v_pk_mul_f32 v[46:47], v[58:59], v[48:49]
	v_cvt_pk_bf16_f32 v52, v52, v53
	v_cvt_pk_bf16_f32 v33, v15, v17
	v_cvt_pk_bf16_f32 v53, v46, v47
	ds_write_b128 v42, v[4:7] offset:10240
	ds_write_b128 v42, v[30:33] offset:10256
	ds_write_b128 v42, v[0:3] offset:19456
	ds_write_b128 v42, v[50:53] offset:19472
	v_lshlrev_b32_e32 v0, 3, v13
	v_lshl_or_b32 v0, v8, 1, v0
	v_ashrrev_i32_e32 v1, 31, v0
	s_and_saveexec_b64 s[16:17], s[12:13]
	s_cbranch_execz .LBB0_426
	v_mul_f32_e32 v2, 0x3fb8aa3b, v28
	v_exp_f32_e32 v4, v2
	v_mul_f32_e32 v2, 0x3fb8aa3b, v34
	v_exp_f32_e32 v5, v2
	v_lshlrev_b64 v[2:3], 8, v[0:1]
	v_lshl_add_u64 v[2:3], v[22:23], 0, v[2:3]
	global_store_dword v[2:3], v4, off
	global_store_dword v[2:3], v5, off offset:256
	s_branch .LBB0_426
